# redundant s_waitcnt lgkmcnt(0) at the head of each MFMA segment deleted (segments are now 32 MFMAs + barrier only)
# speedup vs baseline: 1.0053x; 1.0028x over previous
.Lip_nopf:
	s_add_u32 s38, s42, 0x80
	s_addc_u32 s39, s43, 0
	s_add_i32 s60, 0, 0x10000
	s_add_i32 s61, 0, 0x14000
	v_add_u32_e32 v70, s60, v207
	v_add_u32_e32 v110, s61, v207
	ds_read_b128 v[42:45], v70
	ds_read_b128 v[46:49], v70 offset:1024
	ds_read_b128 v[66:69], v70 offset:2048
	ds_read_b128 v[70:73], v70 offset:3072
	ds_read_b128 v[86:89], v110
	ds_read_b128 v[90:93], v110 offset:1024
	ds_read_b128 v[106:109], v110 offset:2048
	ds_read_b128 v[110:113], v110 offset:3072
	s_add_u32 s58, s19, 0x7ff80
	s_addc_u32 s59, s54, 0
	ds_read_b128 v[130:133], v237
	ds_read_b128 v[134:137], v237 offset:1024
	ds_read_b128 v[154:157], v237 offset:2048
	ds_read_b128 v[158:161], v237 offset:3072
	ds_read_b128 v[178:181], v237 offset:4096
	ds_read_b128 v[182:185], v237 offset:5120
	ds_read_b128 v[186:189], v237 offset:6144
	ds_read_b128 v[190:193], v237 offset:7168
	s_add_i32 m0, s46, 0xc000
	v_lshl_add_u64 v[194:195], s[58:59], 0, v[208:209]
	s_add_u32 s58, s58, 0x40000
	s_addc_u32 s59, s59, 0
	global_load_lds_dwordx4 v[194:195], off
	s_add_i32 m0, s46, 0xe000
	v_lshl_add_u64 v[194:195], s[58:59], 0, v[208:209]
	global_load_lds_dwordx4 v[194:195], off
	s_waitcnt vmcnt(8)
	s_waitcnt lgkmcnt(0)
	s_barrier
	v_mfma_f32_16x16x32_bf16 v[174:177], v[42:45], v[130:133], v[174:177]
	v_mfma_f32_16x16x32_bf16 v[170:173], v[66:69], v[130:133], v[170:173]
	v_mfma_f32_16x16x32_bf16 v[150:153], v[42:45], v[154:157], v[150:153]
	v_mfma_f32_16x16x32_bf16 v[146:149], v[66:69], v[154:157], v[146:149]
	v_mfma_f32_16x16x32_bf16 v[126:129], v[42:45], v[178:181], v[126:129]
	v_mfma_f32_16x16x32_bf16 v[122:125], v[66:69], v[178:181], v[122:125]
	v_mfma_f32_16x16x32_bf16 v[102:105], v[42:45], v[186:189], v[102:105]
	v_mfma_f32_16x16x32_bf16 v[98:101], v[66:69], v[186:189], v[98:101]
	v_mfma_f32_16x16x32_bf16 v[174:177], v[46:49], v[134:137], v[174:177]
	v_mfma_f32_16x16x32_bf16 v[170:173], v[70:73], v[134:137], v[170:173]
	v_mfma_f32_16x16x32_bf16 v[150:153], v[46:49], v[158:161], v[150:153]
	v_mfma_f32_16x16x32_bf16 v[146:149], v[70:73], v[158:161], v[146:149]
	v_mfma_f32_16x16x32_bf16 v[126:129], v[46:49], v[182:185], v[126:129]
	v_mfma_f32_16x16x32_bf16 v[122:125], v[70:73], v[182:185], v[122:125]
	v_mfma_f32_16x16x32_bf16 v[102:105], v[46:49], v[190:193], v[102:105]
	v_mfma_f32_16x16x32_bf16 v[98:101], v[70:73], v[190:193], v[98:101]
	v_mfma_f32_16x16x32_bf16 v[166:169], v[86:89], v[130:133], v[166:169]
	v_mfma_f32_16x16x32_bf16 v[130:133], v[106:109], v[130:133], v[162:165]
	v_mfma_f32_16x16x32_bf16 v[138:141], v[106:109], v[154:157], v[138:141]
	v_mfma_f32_16x16x32_bf16 v[118:121], v[86:89], v[178:181], v[118:121]
	v_mfma_f32_16x16x32_bf16 v[114:117], v[106:109], v[178:181], v[114:117]
	v_mfma_f32_16x16x32_bf16 v[94:97], v[86:89], v[186:189], v[94:97]
	v_mfma_f32_16x16x32_bf16 v[82:85], v[106:109], v[186:189], v[82:85]
	v_mfma_f32_16x16x32_bf16 v[166:169], v[90:93], v[134:137], v[166:169]
	v_mfma_f32_16x16x32_bf16 v[130:133], v[110:113], v[134:137], v[130:133]
	v_mfma_f32_16x16x32_bf16 v[134:137], v[86:89], v[154:157], v[142:145]
	v_mfma_f32_16x16x32_bf16 v[138:141], v[110:113], v[158:161], v[138:141]
	v_mfma_f32_16x16x32_bf16 v[118:121], v[90:93], v[182:185], v[118:121]
	v_mfma_f32_16x16x32_bf16 v[114:117], v[110:113], v[182:185], v[114:117]
	v_mfma_f32_16x16x32_bf16 v[94:97], v[90:93], v[190:193], v[94:97]
	v_mfma_f32_16x16x32_bf16 v[82:85], v[110:113], v[190:193], v[82:85]
	v_mfma_f32_16x16x32_bf16 v[134:137], v[90:93], v[158:161], v[134:137]
	s_barrier
	s_mov_b64 s[58:59], s[40:41]
	ds_read_b128 v[142:145], v237 offset:16384
	ds_read_b128 v[154:157], v237 offset:17408
	ds_read_b128 v[158:161], v237 offset:18432
	ds_read_b128 v[162:165], v237 offset:19456
	ds_read_b128 v[178:181], v237 offset:20480
	ds_read_b128 v[182:185], v237 offset:21504
	ds_read_b128 v[186:189], v237 offset:22528
	ds_read_b128 v[190:193], v237 offset:23552
	s_add_i32 s60, s60, s45
	v_lshl_add_u64 v[194:195], s[58:59], 0, v[202:203]
	s_add_u32 s58, s58, 0x40000
	s_mov_b32 m0, s60
	s_addc_u32 s59, s59, 0
	global_load_lds_dwordx4 v[194:195], off
	s_add_i32 m0, s60, 0x2000
	v_lshl_add_u64 v[194:195], s[58:59], 0, v[202:203]
	s_add_u32 s58, s40, 0x80000
	s_addc_u32 s59, s41, 0
	global_load_lds_dwordx4 v[194:195], off
	s_add_i32 s60, s61, s45
	v_lshl_add_u64 v[194:195], s[58:59], 0, v[202:203]
	s_add_u32 s58, s58, 0x40000
	s_mov_b32 m0, s60
	s_addc_u32 s59, s59, 0
	global_load_lds_dwordx4 v[194:195], off
	s_add_i32 m0, s60, 0x2000
	v_lshl_add_u64 v[194:195], s[58:59], 0, v[202:203]
	s_mov_b64 s[58:59], s[42:43]
	global_load_lds_dwordx4 v[194:195], off
	s_mov_b32 m0, s46
	v_lshl_add_u64 v[194:195], s[58:59], 0, v[208:209]
	s_add_u32 s58, s58, 0x40000
	s_addc_u32 s59, s59, 0
	global_load_lds_dwordx4 v[194:195], off
	s_mov_b32 m0, s47
	v_lshl_add_u64 v[194:195], s[58:59], 0, v[208:209]
	global_load_lds_dwordx4 v[194:195], off
	s_waitcnt vmcnt(8)
	s_waitcnt lgkmcnt(0)
	s_barrier
	v_mfma_f32_16x16x32_bf16 v[78:81], v[42:45], v[142:145], v[78:81]
	v_mfma_f32_16x16x32_bf16 v[74:77], v[66:69], v[142:145], v[74:77]
	v_mfma_f32_16x16x32_bf16 v[54:57], v[42:45], v[158:161], v[54:57]
	v_mfma_f32_16x16x32_bf16 v[50:53], v[66:69], v[158:161], v[50:53]
	v_mfma_f32_16x16x32_bf16 v[30:33], v[42:45], v[178:181], v[30:33]
	v_mfma_f32_16x16x32_bf16 v[26:29], v[66:69], v[178:181], v[26:29]
	v_mfma_f32_16x16x32_bf16 v[14:17], v[42:45], v[186:189], v[14:17]
	v_mfma_f32_16x16x32_bf16 v[10:13], v[66:69], v[186:189], v[10:13]
	v_mfma_f32_16x16x32_bf16 v[78:81], v[46:49], v[154:157], v[78:81]
	v_mfma_f32_16x16x32_bf16 v[74:77], v[70:73], v[154:157], v[74:77]
	v_mfma_f32_16x16x32_bf16 v[54:57], v[46:49], v[162:165], v[54:57]
	v_mfma_f32_16x16x32_bf16 v[50:53], v[70:73], v[162:165], v[50:53]
	v_mfma_f32_16x16x32_bf16 v[30:33], v[46:49], v[182:185], v[30:33]
	v_mfma_f32_16x16x32_bf16 v[26:29], v[70:73], v[182:185], v[26:29]
	v_mfma_f32_16x16x32_bf16 v[14:17], v[46:49], v[190:193], v[14:17]
	v_mfma_f32_16x16x32_bf16 v[10:13], v[70:73], v[190:193], v[10:13]
	v_mfma_f32_16x16x32_bf16 v[38:41], v[86:89], v[158:161], v[38:41]
	v_mfma_f32_16x16x32_bf16 v[34:37], v[106:109], v[158:161], v[34:37]
	v_mfma_f32_16x16x32_bf16 v[22:25], v[86:89], v[178:181], v[22:25]
	v_mfma_f32_16x16x32_bf16 v[18:21], v[106:109], v[178:181], v[18:21]
	v_mfma_f32_16x16x32_bf16 v[6:9], v[86:89], v[186:189], v[6:9]
	v_mfma_f32_16x16x32_bf16 v[2:5], v[106:109], v[186:189], v[2:5]
	v_mfma_f32_16x16x32_bf16 v[42:45], v[86:89], v[142:145], v[62:65]
	v_mfma_f32_16x16x32_bf16 v[46:49], v[106:109], v[142:145], v[58:61]
	v_mfma_f32_16x16x32_bf16 v[38:41], v[90:93], v[162:165], v[38:41]
	v_mfma_f32_16x16x32_bf16 v[34:37], v[110:113], v[162:165], v[34:37]
	v_mfma_f32_16x16x32_bf16 v[22:25], v[90:93], v[182:185], v[22:25]
	v_mfma_f32_16x16x32_bf16 v[18:21], v[110:113], v[182:185], v[18:21]
	v_mfma_f32_16x16x32_bf16 v[6:9], v[90:93], v[190:193], v[6:9]
	v_mfma_f32_16x16x32_bf16 v[2:5], v[110:113], v[190:193], v[2:5]
	v_mfma_f32_16x16x32_bf16 v[42:45], v[90:93], v[154:157], v[42:45]
	v_mfma_f32_16x16x32_bf16 v[46:49], v[110:113], v[154:157], v[46:49]
	s_barrier
	s_add_i32 s58, 0, 0x18000
	s_add_i32 s59, 0, 0x1c000
	v_add_u32_e32 v70, s58, v207
	v_add_u32_e32 v110, s59, v207
	ds_read_b128 v[58:61], v70
	ds_read_b128 v[62:65], v70 offset:1024
	ds_read_b128 v[66:69], v70 offset:2048
	ds_read_b128 v[70:73], v70 offset:3072
	ds_read_b128 v[86:89], v110
	ds_read_b128 v[90:93], v110 offset:1024
	ds_read_b128 v[106:109], v110 offset:2048
	ds_read_b128 v[110:113], v110 offset:3072
	s_add_u32 s42, s42, 0x80000
	s_addc_u32 s43, s43, 0
	ds_read_b128 v[142:145], v237 offset:32768
	ds_read_b128 v[154:157], v237 offset:33792
	ds_read_b128 v[158:161], v237 offset:34816
	ds_read_b128 v[178:181], v237 offset:35840
	ds_read_b128 v[182:185], v237 offset:36864
	ds_read_b128 v[186:189], v237 offset:37888
	ds_read_b128 v[190:193], v237 offset:38912
	ds_read_b128 v[194:197], v237 offset:39936
	s_mov_b32 m0, s48
	v_lshl_add_u64 v[162:163], s[42:43], 0, v[208:209]
	s_add_u32 s42, s42, 0x40000
	s_addc_u32 s43, s43, 0
	global_load_lds_dwordx4 v[162:163], off
	s_mov_b32 m0, s49
	v_lshl_add_u64 v[162:163], s[42:43], 0, v[208:209]
	global_load_lds_dwordx4 v[162:163], off
	s_waitcnt vmcnt(8)
	s_waitcnt lgkmcnt(0)
	s_barrier
	v_mfma_f32_16x16x32_bf16 v[162:165], v[58:61], v[142:145], v[174:177]
	v_mfma_f32_16x16x32_bf16 v[174:177], v[62:65], v[154:157], v[162:165]
	v_mfma_f32_16x16x32_bf16 v[162:165], v[66:69], v[142:145], v[170:173]
	v_mfma_f32_16x16x32_bf16 v[150:153], v[58:61], v[158:161], v[150:153]
	v_mfma_f32_16x16x32_bf16 v[146:149], v[66:69], v[158:161], v[146:149]
	v_mfma_f32_16x16x32_bf16 v[126:129], v[58:61], v[182:185], v[126:129]
	v_mfma_f32_16x16x32_bf16 v[122:125], v[66:69], v[182:185], v[122:125]
	v_mfma_f32_16x16x32_bf16 v[102:105], v[58:61], v[190:193], v[102:105]
	v_mfma_f32_16x16x32_bf16 v[98:101], v[66:69], v[190:193], v[98:101]
	v_mfma_f32_16x16x32_bf16 v[170:173], v[70:73], v[154:157], v[162:165]
	v_mfma_f32_16x16x32_bf16 v[150:153], v[62:65], v[178:181], v[150:153]
	v_mfma_f32_16x16x32_bf16 v[146:149], v[70:73], v[178:181], v[146:149]
	v_mfma_f32_16x16x32_bf16 v[126:129], v[62:65], v[186:189], v[126:129]
	v_mfma_f32_16x16x32_bf16 v[122:125], v[70:73], v[186:189], v[122:125]
	v_mfma_f32_16x16x32_bf16 v[102:105], v[62:65], v[194:197], v[102:105]
	v_mfma_f32_16x16x32_bf16 v[98:101], v[70:73], v[194:197], v[98:101]
	v_mfma_f32_16x16x32_bf16 v[162:165], v[86:89], v[142:145], v[166:169]
	v_mfma_f32_16x16x32_bf16 v[130:133], v[106:109], v[142:145], v[130:133]
	v_mfma_f32_16x16x32_bf16 v[166:169], v[90:93], v[154:157], v[162:165]
	v_mfma_f32_16x16x32_bf16 v[162:165], v[110:113], v[154:157], v[130:133]
	v_mfma_f32_16x16x32_bf16 v[130:133], v[86:89], v[158:161], v[134:137]
	v_mfma_f32_16x16x32_bf16 v[142:145], v[90:93], v[178:181], v[130:133]
	v_mfma_f32_16x16x32_bf16 v[130:133], v[106:109], v[158:161], v[138:141]
	v_mfma_f32_16x16x32_bf16 v[118:121], v[86:89], v[182:185], v[118:121]
	v_mfma_f32_16x16x32_bf16 v[114:117], v[106:109], v[182:185], v[114:117]
	v_mfma_f32_16x16x32_bf16 v[94:97], v[86:89], v[190:193], v[94:97]
	v_mfma_f32_16x16x32_bf16 v[82:85], v[106:109], v[190:193], v[82:85]
	v_mfma_f32_16x16x32_bf16 v[138:141], v[110:113], v[178:181], v[130:133]
	v_mfma_f32_16x16x32_bf16 v[118:121], v[90:93], v[186:189], v[118:121]
	v_mfma_f32_16x16x32_bf16 v[114:117], v[110:113], v[186:189], v[114:117]
	v_mfma_f32_16x16x32_bf16 v[94:97], v[90:93], v[194:197], v[94:97]
	v_mfma_f32_16x16x32_bf16 v[82:85], v[110:113], v[194:197], v[82:85]
	s_barrier
	s_add_u32 s42, s40, 0x80
	s_addc_u32 s43, s41, 0
	ds_read_b128 v[130:133], v237 offset:49152
	ds_read_b128 v[134:137], v237 offset:50176
	ds_read_b128 v[154:157], v237 offset:51200
	ds_read_b128 v[158:161], v237 offset:52224
	ds_read_b128 v[178:181], v237 offset:53248
	ds_read_b128 v[182:185], v237 offset:54272
	ds_read_b128 v[186:189], v237 offset:55296
	ds_read_b128 v[190:193], v237 offset:56320
	s_add_i32 s58, s58, s45
	v_lshl_add_u64 v[194:195], s[42:43], 0, v[202:203]
	s_mov_b32 m0, s58
	s_add_u32 s42, s42, 0x40000
	global_load_lds_dwordx4 v[194:195], off
	s_addc_u32 s43, s43, 0
	s_add_i32 m0, s58, 0x2000
	s_add_u32 s40, s40, 0x80080
	s_addc_u32 s41, s41, 0
	v_lshl_add_u64 v[194:195], s[42:43], 0, v[202:203]
	global_load_lds_dwordx4 v[194:195], off
	s_add_i32 s42, s59, s45
	v_lshl_add_u64 v[194:195], s[40:41], 0, v[202:203]
	s_add_u32 s40, s40, 0x40000
	s_mov_b32 m0, s42
	s_addc_u32 s41, s41, 0
	global_load_lds_dwordx4 v[194:195], off
	s_add_i32 m0, s42, 0x2000
	v_lshl_add_u64 v[194:195], s[40:41], 0, v[202:203]
	global_load_lds_dwordx4 v[194:195], off
	s_mov_b32 m0, s50
	v_lshl_add_u64 v[194:195], s[38:39], 0, v[208:209]
	s_add_u32 s38, s38, 0x40000
	s_addc_u32 s39, s39, 0
	global_load_lds_dwordx4 v[194:195], off
	s_mov_b32 m0, s51
	v_lshl_add_u64 v[194:195], s[38:39], 0, v[208:209]
	global_load_lds_dwordx4 v[194:195], off
	s_waitcnt vmcnt(8)
	s_waitcnt lgkmcnt(0)
	s_barrier
	v_mfma_f32_16x16x32_bf16 v[78:81], v[58:61], v[130:133], v[78:81]
	v_mfma_f32_16x16x32_bf16 v[74:77], v[66:69], v[130:133], v[74:77]
	v_mfma_f32_16x16x32_bf16 v[54:57], v[58:61], v[154:157], v[54:57]
	v_mfma_f32_16x16x32_bf16 v[50:53], v[66:69], v[154:157], v[50:53]
	v_mfma_f32_16x16x32_bf16 v[30:33], v[58:61], v[178:181], v[30:33]
	v_mfma_f32_16x16x32_bf16 v[26:29], v[66:69], v[178:181], v[26:29]
	v_mfma_f32_16x16x32_bf16 v[14:17], v[58:61], v[186:189], v[14:17]
	v_mfma_f32_16x16x32_bf16 v[10:13], v[66:69], v[186:189], v[10:13]
	v_mfma_f32_16x16x32_bf16 v[78:81], v[62:65], v[134:137], v[78:81]
	v_mfma_f32_16x16x32_bf16 v[74:77], v[70:73], v[134:137], v[74:77]
	v_mfma_f32_16x16x32_bf16 v[54:57], v[62:65], v[158:161], v[54:57]
	v_mfma_f32_16x16x32_bf16 v[50:53], v[70:73], v[158:161], v[50:53]
	v_mfma_f32_16x16x32_bf16 v[30:33], v[62:65], v[182:185], v[30:33]
	v_mfma_f32_16x16x32_bf16 v[26:29], v[70:73], v[182:185], v[26:29]
	v_mfma_f32_16x16x32_bf16 v[14:17], v[62:65], v[190:193], v[14:17]
	v_mfma_f32_16x16x32_bf16 v[10:13], v[70:73], v[190:193], v[10:13]
	v_mfma_f32_16x16x32_bf16 v[42:45], v[86:89], v[130:133], v[42:45]
	v_mfma_f32_16x16x32_bf16 v[62:65], v[90:93], v[134:137], v[42:45]
	v_mfma_f32_16x16x32_bf16 v[42:45], v[106:109], v[130:133], v[46:49]
	v_mfma_f32_16x16x32_bf16 v[38:41], v[86:89], v[154:157], v[38:41]
	v_mfma_f32_16x16x32_bf16 v[34:37], v[106:109], v[154:157], v[34:37]
	v_mfma_f32_16x16x32_bf16 v[22:25], v[86:89], v[178:181], v[22:25]
	v_mfma_f32_16x16x32_bf16 v[18:21], v[106:109], v[178:181], v[18:21]
	v_mfma_f32_16x16x32_bf16 v[6:9], v[86:89], v[186:189], v[6:9]
	v_mfma_f32_16x16x32_bf16 v[2:5], v[106:109], v[186:189], v[2:5]
	v_mfma_f32_16x16x32_bf16 v[58:61], v[110:113], v[134:137], v[42:45]
	v_mfma_f32_16x16x32_bf16 v[38:41], v[90:93], v[158:161], v[38:41]
	v_mfma_f32_16x16x32_bf16 v[34:37], v[110:113], v[158:161], v[34:37]
	v_mfma_f32_16x16x32_bf16 v[22:25], v[90:93], v[182:185], v[22:25]
	v_mfma_f32_16x16x32_bf16 v[18:21], v[110:113], v[182:185], v[18:21]
	v_mfma_f32_16x16x32_bf16 v[6:9], v[90:93], v[190:193], v[6:9]
	v_mfma_f32_16x16x32_bf16 v[2:5], v[110:113], v[190:193], v[2:5]
	s_barrier
	s_add_i32 s57, s57, 2
	s_add_u32 s19, s19, 0x100
	s_addc_u32 s54, s54, 0
	s_add_u32 s55, s55, 0x100
	s_addc_u32 s56, s56, 0
	s_cmp_gt_u32 s57, 29
	s_cbranch_scc0 .LBB0_293
	s_and_b64 vcc, exec, s[16:17]
	s_cbranch_vccz .LBB0_296
	s_barrier

.LBB0_1013:
	s_add_i32 s78, s10, 2
	s_cmp_eq_u32 s71, s10
	s_cselect_b32 s46, s4, s28
	s_cselect_b32 s47, s5, s29
	s_cselect_b32 s44, s42, s76
	s_cselect_b32 s45, s43, s77
	s_add_u32 s10, s46, 0x80
	s_addc_u32 s11, s47, 0
	s_add_i32 s79, 0, 0x10000
	s_add_i32 s82, 0, 0x14000
	v_add_u32_e32 v142, s79, v179
	v_add_u32_e32 v160, s82, v179
	ds_read_b128 v[130:133], v142
	ds_read_b128 v[134:137], v142 offset:1024
	ds_read_b128 v[138:141], v142 offset:2048
	ds_read_b128 v[142:145], v142 offset:3072
	ds_read_b128 v[146:149], v160
	ds_read_b128 v[150:153], v160 offset:1024
	ds_read_b128 v[154:157], v160 offset:2048
	ds_read_b128 v[160:163], v160 offset:3072
	s_add_u32 s80, s28, 0x7ff80
	v_add_u32_e32 v240, 0, v178
	s_addc_u32 s81, s29, 0
	ds_read_b128 v[164:167], v240
	ds_read_b128 v[168:171], v240 offset:1024
	ds_read_b128 v[172:175], v240 offset:2048
	ds_read_b128 v[212:215], v240 offset:3072
	ds_read_b128 v[216:219], v240 offset:4096
	ds_read_b128 v[220:223], v240 offset:5120
	ds_read_b128 v[224:227], v240 offset:6144
	ds_read_b128 v[236:239], v240 offset:7168
	s_add_i32 m0, s49, 0xc000
	v_lshl_add_u64 v[176:177], s[80:81], 0, v[158:159]
	s_add_u32 s80, s80, 0x40000
	s_addc_u32 s81, s81, 0
	global_load_lds_dwordx4 v[176:177], off
	s_add_i32 m0, s49, 0xe000
	v_lshl_add_u64 v[176:177], s[80:81], 0, v[158:159]
	global_load_lds_dwordx4 v[176:177], off
	s_waitcnt vmcnt(8)
	s_waitcnt lgkmcnt(0)
	s_barrier
	v_mfma_f32_16x16x32_bf16 v[126:129], v[130:133], v[164:167], v[126:129]
	v_mfma_f32_16x16x32_bf16 v[122:125], v[138:141], v[164:167], v[122:125]
	v_mfma_f32_16x16x32_bf16 v[114:117], v[130:133], v[172:175], v[114:117]
	v_mfma_f32_16x16x32_bf16 v[106:109], v[138:141], v[172:175], v[106:109]
	v_mfma_f32_16x16x32_bf16 v[98:101], v[130:133], v[216:219], v[98:101]
	v_mfma_f32_16x16x32_bf16 v[90:93], v[138:141], v[216:219], v[90:93]
	v_mfma_f32_16x16x32_bf16 v[82:85], v[130:133], v[224:227], v[82:85]
	v_mfma_f32_16x16x32_bf16 v[74:77], v[138:141], v[224:227], v[74:77]
	v_mfma_f32_16x16x32_bf16 v[126:129], v[134:137], v[168:171], v[126:129]
	v_mfma_f32_16x16x32_bf16 v[122:125], v[142:145], v[168:171], v[122:125]
	v_mfma_f32_16x16x32_bf16 v[114:117], v[134:137], v[212:215], v[114:117]
	v_mfma_f32_16x16x32_bf16 v[106:109], v[142:145], v[212:215], v[106:109]
	v_mfma_f32_16x16x32_bf16 v[98:101], v[134:137], v[220:223], v[98:101]
	v_mfma_f32_16x16x32_bf16 v[90:93], v[142:145], v[220:223], v[90:93]
	v_mfma_f32_16x16x32_bf16 v[82:85], v[134:137], v[236:239], v[82:85]
	v_mfma_f32_16x16x32_bf16 v[74:77], v[142:145], v[236:239], v[74:77]
	v_mfma_f32_16x16x32_bf16 v[118:121], v[146:149], v[164:167], v[118:121]
	v_mfma_f32_16x16x32_bf16 v[110:113], v[154:157], v[164:167], v[110:113]
	v_mfma_f32_16x16x32_bf16 v[102:105], v[146:149], v[172:175], v[102:105]
	v_mfma_f32_16x16x32_bf16 v[94:97], v[154:157], v[172:175], v[94:97]
	v_mfma_f32_16x16x32_bf16 v[86:89], v[146:149], v[216:219], v[86:89]
	v_mfma_f32_16x16x32_bf16 v[78:81], v[154:157], v[216:219], v[78:81]
	v_mfma_f32_16x16x32_bf16 v[70:73], v[146:149], v[224:227], v[70:73]
	v_mfma_f32_16x16x32_bf16 v[66:69], v[154:157], v[224:227], v[66:69]
	v_mfma_f32_16x16x32_bf16 v[118:121], v[150:153], v[168:171], v[118:121]
	v_mfma_f32_16x16x32_bf16 v[110:113], v[160:163], v[168:171], v[110:113]
	v_mfma_f32_16x16x32_bf16 v[102:105], v[150:153], v[212:215], v[102:105]
	v_mfma_f32_16x16x32_bf16 v[94:97], v[160:163], v[212:215], v[94:97]
	v_mfma_f32_16x16x32_bf16 v[86:89], v[150:153], v[220:223], v[86:89]
	v_mfma_f32_16x16x32_bf16 v[78:81], v[160:163], v[220:223], v[78:81]
	v_mfma_f32_16x16x32_bf16 v[70:73], v[150:153], v[236:239], v[70:73]
	v_mfma_f32_16x16x32_bf16 v[66:69], v[160:163], v[236:239], v[66:69]
	s_barrier
	s_mov_b64 s[80:81], s[44:45]
	ds_read_b128 v[164:167], v240 offset:16384
	ds_read_b128 v[168:171], v240 offset:17408
	ds_read_b128 v[172:175], v240 offset:18432
	ds_read_b128 v[212:215], v240 offset:19456
	ds_read_b128 v[216:219], v240 offset:20480
	ds_read_b128 v[220:223], v240 offset:21504
	ds_read_b128 v[224:227], v240 offset:22528
	ds_read_b128 v[236:239], v240 offset:23552
	s_add_i32 s79, s79, s48
	v_lshl_add_u64 v[176:177], s[80:81], 0, v[202:203]
	s_add_u32 s80, s80, 0x30000
	s_mov_b32 m0, s79
	s_addc_u32 s81, s81, 0
	global_load_lds_dwordx4 v[176:177], off
	s_add_i32 m0, s79, 0x2000
	v_lshl_add_u64 v[176:177], s[80:81], 0, v[202:203]
	s_add_u32 s80, s44, 0x60000
	s_addc_u32 s81, s45, 0
	global_load_lds_dwordx4 v[176:177], off
	s_add_i32 s79, s82, s48
	v_lshl_add_u64 v[176:177], s[80:81], 0, v[202:203]
	s_add_u32 s80, s80, 0x30000
	s_mov_b32 m0, s79
	s_addc_u32 s81, s81, 0
	global_load_lds_dwordx4 v[176:177], off
	s_add_i32 m0, s79, 0x2000
	v_lshl_add_u64 v[176:177], s[80:81], 0, v[202:203]
	s_mov_b64 s[80:81], s[46:47]
	global_load_lds_dwordx4 v[176:177], off
	s_mov_b32 m0, s49
	v_lshl_add_u64 v[176:177], s[80:81], 0, v[158:159]
	s_add_u32 s80, s80, 0x40000
	s_addc_u32 s81, s81, 0
	global_load_lds_dwordx4 v[176:177], off
	s_mov_b32 m0, s50
	v_lshl_add_u64 v[176:177], s[80:81], 0, v[158:159]
	global_load_lds_dwordx4 v[176:177], off
	s_waitcnt vmcnt(8)
	s_waitcnt lgkmcnt(0)
	s_barrier
	v_mfma_f32_16x16x32_bf16 v[62:65], v[130:133], v[164:167], v[62:65]
	v_mfma_f32_16x16x32_bf16 v[58:61], v[138:141], v[164:167], v[58:61]
	v_mfma_f32_16x16x32_bf16 v[50:53], v[130:133], v[172:175], v[50:53]
	v_mfma_f32_16x16x32_bf16 v[42:45], v[138:141], v[172:175], v[42:45]
	v_mfma_f32_16x16x32_bf16 v[34:37], v[130:133], v[216:219], v[34:37]
	v_mfma_f32_16x16x32_bf16 v[26:29], v[138:141], v[216:219], v[26:29]
	v_mfma_f32_16x16x32_bf16 v[18:21], v[130:133], v[224:227], v[18:21]
	v_mfma_f32_16x16x32_bf16 v[10:13], v[138:141], v[224:227], v[10:13]
	v_mfma_f32_16x16x32_bf16 v[62:65], v[134:137], v[168:171], v[62:65]
	v_mfma_f32_16x16x32_bf16 v[58:61], v[142:145], v[168:171], v[58:61]
	v_mfma_f32_16x16x32_bf16 v[50:53], v[134:137], v[212:215], v[50:53]
	v_mfma_f32_16x16x32_bf16 v[42:45], v[142:145], v[212:215], v[42:45]
	v_mfma_f32_16x16x32_bf16 v[34:37], v[134:137], v[220:223], v[34:37]
	v_mfma_f32_16x16x32_bf16 v[26:29], v[142:145], v[220:223], v[26:29]
	v_mfma_f32_16x16x32_bf16 v[18:21], v[134:137], v[236:239], v[18:21]
	v_mfma_f32_16x16x32_bf16 v[10:13], v[142:145], v[236:239], v[10:13]
	v_mfma_f32_16x16x32_bf16 v[54:57], v[146:149], v[164:167], v[54:57]
	v_mfma_f32_16x16x32_bf16 v[46:49], v[154:157], v[164:167], v[46:49]
	v_mfma_f32_16x16x32_bf16 v[38:41], v[146:149], v[172:175], v[38:41]
	v_mfma_f32_16x16x32_bf16 v[30:33], v[154:157], v[172:175], v[30:33]
	v_mfma_f32_16x16x32_bf16 v[22:25], v[146:149], v[216:219], v[22:25]
	v_mfma_f32_16x16x32_bf16 v[14:17], v[154:157], v[216:219], v[14:17]
	v_mfma_f32_16x16x32_bf16 v[6:9], v[146:149], v[224:227], v[6:9]
	v_mfma_f32_16x16x32_bf16 v[2:5], v[154:157], v[224:227], v[2:5]
	v_mfma_f32_16x16x32_bf16 v[54:57], v[150:153], v[168:171], v[54:57]
	v_mfma_f32_16x16x32_bf16 v[46:49], v[160:163], v[168:171], v[46:49]
	v_mfma_f32_16x16x32_bf16 v[38:41], v[150:153], v[212:215], v[38:41]
	v_mfma_f32_16x16x32_bf16 v[30:33], v[160:163], v[212:215], v[30:33]
	v_mfma_f32_16x16x32_bf16 v[22:25], v[150:153], v[220:223], v[22:25]
	v_mfma_f32_16x16x32_bf16 v[14:17], v[160:163], v[220:223], v[14:17]
	v_mfma_f32_16x16x32_bf16 v[6:9], v[150:153], v[236:239], v[6:9]
	v_mfma_f32_16x16x32_bf16 v[2:5], v[160:163], v[236:239], v[2:5]
	s_barrier
	s_add_i32 s79, 0, 0x18000
	s_add_i32 s80, 0, 0x1c000
	v_add_u32_e32 v142, s79, v179
	v_add_u32_e32 v160, s80, v179
	ds_read_b128 v[130:133], v142
	ds_read_b128 v[134:137], v142 offset:1024
	ds_read_b128 v[138:141], v142 offset:2048
	ds_read_b128 v[142:145], v142 offset:3072
	ds_read_b128 v[146:149], v160
	ds_read_b128 v[150:153], v160 offset:1024
	ds_read_b128 v[154:157], v160 offset:2048
	ds_read_b128 v[160:163], v160 offset:3072
	s_add_u32 s46, s46, 0x80000
	s_addc_u32 s47, s47, 0
	ds_read_b128 v[164:167], v240 offset:32768
	ds_read_b128 v[168:171], v240 offset:33792
	ds_read_b128 v[172:175], v240 offset:34816
	ds_read_b128 v[212:215], v240 offset:35840
	ds_read_b128 v[216:219], v240 offset:36864
	ds_read_b128 v[220:223], v240 offset:37888
	ds_read_b128 v[224:227], v240 offset:38912
	ds_read_b128 v[236:239], v240 offset:39936
	s_mov_b32 m0, s51
	v_lshl_add_u64 v[176:177], s[46:47], 0, v[158:159]
	s_add_u32 s46, s46, 0x40000
	s_addc_u32 s47, s47, 0
	global_load_lds_dwordx4 v[176:177], off
	s_mov_b32 m0, s52
	v_lshl_add_u64 v[176:177], s[46:47], 0, v[158:159]
	global_load_lds_dwordx4 v[176:177], off
	s_waitcnt vmcnt(8)
	s_waitcnt lgkmcnt(0)
	s_barrier
	v_mfma_f32_16x16x32_bf16 v[126:129], v[130:133], v[164:167], v[126:129]
	v_mfma_f32_16x16x32_bf16 v[122:125], v[138:141], v[164:167], v[122:125]
	v_mfma_f32_16x16x32_bf16 v[114:117], v[130:133], v[172:175], v[114:117]
	v_mfma_f32_16x16x32_bf16 v[106:109], v[138:141], v[172:175], v[106:109]
	v_mfma_f32_16x16x32_bf16 v[98:101], v[130:133], v[216:219], v[98:101]
	v_mfma_f32_16x16x32_bf16 v[90:93], v[138:141], v[216:219], v[90:93]
	v_mfma_f32_16x16x32_bf16 v[82:85], v[130:133], v[224:227], v[82:85]
	v_mfma_f32_16x16x32_bf16 v[74:77], v[138:141], v[224:227], v[74:77]
	v_mfma_f32_16x16x32_bf16 v[126:129], v[134:137], v[168:171], v[126:129]
	v_mfma_f32_16x16x32_bf16 v[122:125], v[142:145], v[168:171], v[122:125]
	v_mfma_f32_16x16x32_bf16 v[114:117], v[134:137], v[212:215], v[114:117]
	v_mfma_f32_16x16x32_bf16 v[106:109], v[142:145], v[212:215], v[106:109]
	v_mfma_f32_16x16x32_bf16 v[98:101], v[134:137], v[220:223], v[98:101]
	v_mfma_f32_16x16x32_bf16 v[90:93], v[142:145], v[220:223], v[90:93]
	v_mfma_f32_16x16x32_bf16 v[82:85], v[134:137], v[236:239], v[82:85]
	v_mfma_f32_16x16x32_bf16 v[74:77], v[142:145], v[236:239], v[74:77]
	v_mfma_f32_16x16x32_bf16 v[118:121], v[146:149], v[164:167], v[118:121]
	v_mfma_f32_16x16x32_bf16 v[110:113], v[154:157], v[164:167], v[110:113]
	v_mfma_f32_16x16x32_bf16 v[102:105], v[146:149], v[172:175], v[102:105]
	v_mfma_f32_16x16x32_bf16 v[94:97], v[154:157], v[172:175], v[94:97]
	v_mfma_f32_16x16x32_bf16 v[86:89], v[146:149], v[216:219], v[86:89]
	v_mfma_f32_16x16x32_bf16 v[78:81], v[154:157], v[216:219], v[78:81]
	v_mfma_f32_16x16x32_bf16 v[70:73], v[146:149], v[224:227], v[70:73]
	v_mfma_f32_16x16x32_bf16 v[66:69], v[154:157], v[224:227], v[66:69]
	v_mfma_f32_16x16x32_bf16 v[118:121], v[150:153], v[168:171], v[118:121]
	v_mfma_f32_16x16x32_bf16 v[110:113], v[160:163], v[168:171], v[110:113]
	v_mfma_f32_16x16x32_bf16 v[102:105], v[150:153], v[212:215], v[102:105]
	v_mfma_f32_16x16x32_bf16 v[94:97], v[160:163], v[212:215], v[94:97]
	v_mfma_f32_16x16x32_bf16 v[86:89], v[150:153], v[220:223], v[86:89]
	v_mfma_f32_16x16x32_bf16 v[78:81], v[160:163], v[220:223], v[78:81]
	v_mfma_f32_16x16x32_bf16 v[70:73], v[150:153], v[236:239], v[70:73]
	v_mfma_f32_16x16x32_bf16 v[66:69], v[160:163], v[236:239], v[66:69]
	s_barrier
	s_add_u32 s46, s44, 0x80
	s_addc_u32 s47, s45, 0
	ds_read_b128 v[164:167], v240 offset:49152
	ds_read_b128 v[168:171], v240 offset:50176
	ds_read_b128 v[172:175], v240 offset:51200
	ds_read_b128 v[212:215], v240 offset:52224
	ds_read_b128 v[216:219], v240 offset:53248
	ds_read_b128 v[220:223], v240 offset:54272
	ds_read_b128 v[224:227], v240 offset:55296
	ds_read_b128 v[236:239], v240 offset:56320
	s_add_i32 s79, s79, s48
	v_lshl_add_u64 v[176:177], s[46:47], 0, v[202:203]
	s_mov_b32 m0, s79
	s_add_u32 s46, s46, 0x30000
	global_load_lds_dwordx4 v[176:177], off
	s_addc_u32 s47, s47, 0
	s_add_i32 m0, s79, 0x2000
	s_add_u32 s44, s44, 0x60080
	s_addc_u32 s45, s45, 0
	v_lshl_add_u64 v[176:177], s[46:47], 0, v[202:203]
	global_load_lds_dwordx4 v[176:177], off
	s_add_i32 s46, s80, s48
	v_lshl_add_u64 v[176:177], s[44:45], 0, v[202:203]
	s_add_u32 s44, s44, 0x30000
	s_mov_b32 m0, s46
	s_addc_u32 s45, s45, 0
	global_load_lds_dwordx4 v[176:177], off
	s_add_i32 m0, s46, 0x2000
	v_lshl_add_u64 v[176:177], s[44:45], 0, v[202:203]
	global_load_lds_dwordx4 v[176:177], off
	s_mov_b32 m0, s53
	v_lshl_add_u64 v[176:177], s[10:11], 0, v[158:159]
	s_add_u32 s10, s10, 0x40000
	s_addc_u32 s11, s11, 0
	global_load_lds_dwordx4 v[176:177], off
	s_mov_b32 m0, s54
	v_lshl_add_u64 v[176:177], s[10:11], 0, v[158:159]
	global_load_lds_dwordx4 v[176:177], off
	s_waitcnt vmcnt(8)
	s_waitcnt lgkmcnt(0)
	s_barrier
	v_mfma_f32_16x16x32_bf16 v[62:65], v[130:133], v[164:167], v[62:65]
	v_mfma_f32_16x16x32_bf16 v[58:61], v[138:141], v[164:167], v[58:61]
	v_mfma_f32_16x16x32_bf16 v[50:53], v[130:133], v[172:175], v[50:53]
	v_mfma_f32_16x16x32_bf16 v[42:45], v[138:141], v[172:175], v[42:45]
	v_mfma_f32_16x16x32_bf16 v[34:37], v[130:133], v[216:219], v[34:37]
	v_mfma_f32_16x16x32_bf16 v[26:29], v[138:141], v[216:219], v[26:29]
	v_mfma_f32_16x16x32_bf16 v[18:21], v[130:133], v[224:227], v[18:21]
	v_mfma_f32_16x16x32_bf16 v[10:13], v[138:141], v[224:227], v[10:13]
	v_mfma_f32_16x16x32_bf16 v[62:65], v[134:137], v[168:171], v[62:65]
	v_mfma_f32_16x16x32_bf16 v[58:61], v[142:145], v[168:171], v[58:61]
	v_mfma_f32_16x16x32_bf16 v[50:53], v[134:137], v[212:215], v[50:53]
	v_mfma_f32_16x16x32_bf16 v[42:45], v[142:145], v[212:215], v[42:45]
	v_mfma_f32_16x16x32_bf16 v[34:37], v[134:137], v[220:223], v[34:37]
	v_mfma_f32_16x16x32_bf16 v[26:29], v[142:145], v[220:223], v[26:29]
	v_mfma_f32_16x16x32_bf16 v[18:21], v[134:137], v[236:239], v[18:21]
	v_mfma_f32_16x16x32_bf16 v[10:13], v[142:145], v[236:239], v[10:13]
	v_mfma_f32_16x16x32_bf16 v[54:57], v[146:149], v[164:167], v[54:57]
	v_mfma_f32_16x16x32_bf16 v[46:49], v[154:157], v[164:167], v[46:49]
	v_mfma_f32_16x16x32_bf16 v[38:41], v[146:149], v[172:175], v[38:41]
	v_mfma_f32_16x16x32_bf16 v[30:33], v[154:157], v[172:175], v[30:33]
	v_mfma_f32_16x16x32_bf16 v[22:25], v[146:149], v[216:219], v[22:25]
	v_mfma_f32_16x16x32_bf16 v[14:17], v[154:157], v[216:219], v[14:17]
	v_mfma_f32_16x16x32_bf16 v[6:9], v[146:149], v[224:227], v[6:9]
	v_mfma_f32_16x16x32_bf16 v[2:5], v[154:157], v[224:227], v[2:5]
	v_mfma_f32_16x16x32_bf16 v[54:57], v[150:153], v[168:171], v[54:57]
	v_mfma_f32_16x16x32_bf16 v[46:49], v[160:163], v[168:171], v[46:49]
	v_mfma_f32_16x16x32_bf16 v[38:41], v[150:153], v[212:215], v[38:41]
	v_mfma_f32_16x16x32_bf16 v[30:33], v[160:163], v[212:215], v[30:33]
	v_mfma_f32_16x16x32_bf16 v[22:25], v[150:153], v[220:223], v[22:25]
	v_mfma_f32_16x16x32_bf16 v[14:17], v[160:163], v[220:223], v[14:17]
	v_mfma_f32_16x16x32_bf16 v[6:9], v[150:153], v[236:239], v[6:9]
	v_mfma_f32_16x16x32_bf16 v[2:5], v[160:163], v[236:239], v[2:5]
	s_barrier
	s_add_u32 s28, s28, 0x100
	s_addc_u32 s29, s29, 0
	s_add_u32 s76, s76, 0x100
	s_addc_u32 s77, s77, 0
	s_cmp_ge_i32 s78, s69
	s_mov_b32 s10, s78
	s_cbranch_scc0 .LBB0_1013
	s_and_b64 vcc, exec, s[18:19]
	s_cbranch_vccz .LBB0_1016
	s_barrier

.Lg0_nopf:
	s_add_u32 s10, s46, 0x80
	s_addc_u32 s11, s47, 0
	s_add_i32 s29, 0, 0x10000
	s_add_i32 s78, 0, 0x14000
	v_add_u32_e32 v142, s29, v179
	v_add_u32_e32 v160, s78, v179
	ds_read_b128 v[130:133], v142
	ds_read_b128 v[134:137], v142 offset:1024
	ds_read_b128 v[138:141], v142 offset:2048
	ds_read_b128 v[142:145], v142 offset:3072
	ds_read_b128 v[146:149], v160
	ds_read_b128 v[150:153], v160 offset:1024
	ds_read_b128 v[154:157], v160 offset:2048
	ds_read_b128 v[160:163], v160 offset:3072
	s_add_u32 s76, s74, 0x7ff80
	v_add_u32_e32 v200, 0, v178
	s_addc_u32 s77, s75, 0
	ds_read_b128 v[164:167], v200
	ds_read_b128 v[168:171], v200 offset:1024
	ds_read_b128 v[172:175], v200 offset:2048
	ds_read_b128 v[180:183], v200 offset:3072
	ds_read_b128 v[184:187], v200 offset:4096
	ds_read_b128 v[188:191], v200 offset:5120
	ds_read_b128 v[192:195], v200 offset:6144
	ds_read_b128 v[196:199], v200 offset:7168
	s_add_i32 m0, s49, 0xc000
	v_lshl_add_u64 v[176:177], s[76:77], 0, v[158:159]
	s_add_u32 s76, s76, 0x40000
	s_addc_u32 s77, s77, 0
	global_load_lds_dwordx4 v[176:177], off
	s_add_i32 m0, s49, 0xe000
	v_lshl_add_u64 v[176:177], s[76:77], 0, v[158:159]
	global_load_lds_dwordx4 v[176:177], off
	s_waitcnt vmcnt(8)
	s_waitcnt lgkmcnt(0)
	s_barrier
	v_mfma_i32_16x16x64_i8 v[126:129], v[130:133], v[164:167], v[126:129]
	v_mfma_i32_16x16x64_i8 v[122:125], v[138:141], v[164:167], v[122:125]
	v_mfma_i32_16x16x64_i8 v[118:121], v[130:133], v[172:175], v[118:121]
	v_mfma_i32_16x16x64_i8 v[114:117], v[138:141], v[172:175], v[114:117]
	v_mfma_i32_16x16x64_i8 v[102:105], v[130:133], v[184:187], v[102:105]
	v_mfma_i32_16x16x64_i8 v[98:101], v[138:141], v[184:187], v[98:101]
	v_mfma_i32_16x16x64_i8 v[86:89], v[130:133], v[192:195], v[86:89]
	v_mfma_i32_16x16x64_i8 v[82:85], v[138:141], v[192:195], v[82:85]
	v_mfma_i32_16x16x64_i8 v[126:129], v[134:137], v[168:171], v[126:129]
	v_mfma_i32_16x16x64_i8 v[122:125], v[142:145], v[168:171], v[122:125]
	v_mfma_i32_16x16x64_i8 v[118:121], v[134:137], v[180:183], v[118:121]
	v_mfma_i32_16x16x64_i8 v[114:117], v[142:145], v[180:183], v[114:117]
	v_mfma_i32_16x16x64_i8 v[102:105], v[134:137], v[188:191], v[102:105]
	v_mfma_i32_16x16x64_i8 v[98:101], v[142:145], v[188:191], v[98:101]
	v_mfma_i32_16x16x64_i8 v[86:89], v[134:137], v[196:199], v[86:89]
	v_mfma_i32_16x16x64_i8 v[82:85], v[142:145], v[196:199], v[82:85]
	v_mfma_i32_16x16x64_i8 v[110:113], v[146:149], v[164:167], v[110:113]
	v_mfma_i32_16x16x64_i8 v[106:109], v[154:157], v[164:167], v[106:109]
	v_mfma_i32_16x16x64_i8 v[94:97], v[146:149], v[172:175], v[94:97]
	v_mfma_i32_16x16x64_i8 v[90:93], v[154:157], v[172:175], v[90:93]
	v_mfma_i32_16x16x64_i8 v[78:81], v[146:149], v[184:187], v[78:81]
	v_mfma_i32_16x16x64_i8 v[74:77], v[154:157], v[184:187], v[74:77]
	v_mfma_i32_16x16x64_i8 v[70:73], v[146:149], v[192:195], v[70:73]
	v_mfma_i32_16x16x64_i8 v[66:69], v[154:157], v[192:195], v[66:69]
	v_mfma_i32_16x16x64_i8 v[110:113], v[150:153], v[168:171], v[110:113]
	v_mfma_i32_16x16x64_i8 v[106:109], v[160:163], v[168:171], v[106:109]
	v_mfma_i32_16x16x64_i8 v[94:97], v[150:153], v[180:183], v[94:97]
	v_mfma_i32_16x16x64_i8 v[90:93], v[160:163], v[180:183], v[90:93]
	v_mfma_i32_16x16x64_i8 v[78:81], v[150:153], v[188:191], v[78:81]
	v_mfma_i32_16x16x64_i8 v[74:77], v[160:163], v[188:191], v[74:77]
	v_mfma_i32_16x16x64_i8 v[70:73], v[150:153], v[196:199], v[70:73]
	v_mfma_i32_16x16x64_i8 v[66:69], v[160:163], v[196:199], v[66:69]
	s_barrier
	s_mov_b64 s[76:77], s[44:45]
	ds_read_b128 v[164:167], v200 offset:16384
	ds_read_b128 v[168:171], v200 offset:17408
	ds_read_b128 v[172:175], v200 offset:18432
	ds_read_b128 v[180:183], v200 offset:19456
	ds_read_b128 v[184:187], v200 offset:20480
	ds_read_b128 v[188:191], v200 offset:21504
	ds_read_b128 v[192:195], v200 offset:22528
	ds_read_b128 v[196:199], v200 offset:23552
	s_add_i32 s29, s29, s48
	v_lshl_add_u64 v[176:177], s[76:77], 0, v[202:203]
	s_add_u32 s76, s76, 0x30000
	s_mov_b32 m0, s29
	s_addc_u32 s77, s77, 0
	global_load_lds_dwordx4 v[176:177], off
	s_add_i32 m0, s29, 0x2000
	v_lshl_add_u64 v[176:177], s[76:77], 0, v[202:203]
	s_add_u32 s76, s44, 0x60000
	s_addc_u32 s77, s45, 0
	global_load_lds_dwordx4 v[176:177], off
	s_add_i32 s29, s78, s48
	v_lshl_add_u64 v[176:177], s[76:77], 0, v[202:203]
	s_add_u32 s76, s76, 0x30000
	s_mov_b32 m0, s29
	s_addc_u32 s77, s77, 0
	global_load_lds_dwordx4 v[176:177], off
	s_add_i32 m0, s29, 0x2000
	v_lshl_add_u64 v[176:177], s[76:77], 0, v[202:203]
	s_mov_b64 s[76:77], s[46:47]
	global_load_lds_dwordx4 v[176:177], off
	s_mov_b32 m0, s49
	v_lshl_add_u64 v[176:177], s[76:77], 0, v[158:159]
	s_add_u32 s76, s76, 0x40000
	s_addc_u32 s77, s77, 0
	global_load_lds_dwordx4 v[176:177], off
	s_mov_b32 m0, s50
	v_lshl_add_u64 v[176:177], s[76:77], 0, v[158:159]
	global_load_lds_dwordx4 v[176:177], off
	s_waitcnt vmcnt(8)
	s_waitcnt lgkmcnt(0)
	s_barrier
	v_mfma_i32_16x16x64_i8 v[62:65], v[130:133], v[164:167], v[62:65]
	v_mfma_i32_16x16x64_i8 v[58:61], v[138:141], v[164:167], v[58:61]
	v_mfma_i32_16x16x64_i8 v[54:57], v[130:133], v[172:175], v[54:57]
	v_mfma_i32_16x16x64_i8 v[50:53], v[138:141], v[172:175], v[50:53]
	v_mfma_i32_16x16x64_i8 v[38:41], v[130:133], v[184:187], v[38:41]
	v_mfma_i32_16x16x64_i8 v[34:37], v[138:141], v[184:187], v[34:37]
	v_mfma_i32_16x16x64_i8 v[14:17], v[130:133], v[192:195], v[14:17]
	v_mfma_i32_16x16x64_i8 v[10:13], v[138:141], v[192:195], v[10:13]
	v_mfma_i32_16x16x64_i8 v[62:65], v[134:137], v[168:171], v[62:65]
	v_mfma_i32_16x16x64_i8 v[58:61], v[142:145], v[168:171], v[58:61]
	v_mfma_i32_16x16x64_i8 v[54:57], v[134:137], v[180:183], v[54:57]
	v_mfma_i32_16x16x64_i8 v[50:53], v[142:145], v[180:183], v[50:53]
	v_mfma_i32_16x16x64_i8 v[38:41], v[134:137], v[188:191], v[38:41]
	v_mfma_i32_16x16x64_i8 v[34:37], v[142:145], v[188:191], v[34:37]
	v_mfma_i32_16x16x64_i8 v[14:17], v[134:137], v[196:199], v[14:17]
	v_mfma_i32_16x16x64_i8 v[10:13], v[142:145], v[196:199], v[10:13]
	v_mfma_i32_16x16x64_i8 v[46:49], v[146:149], v[164:167], v[46:49]
	v_mfma_i32_16x16x64_i8 v[42:45], v[154:157], v[164:167], v[42:45]
	v_mfma_i32_16x16x64_i8 v[30:33], v[146:149], v[172:175], v[30:33]
	v_mfma_i32_16x16x64_i8 v[26:29], v[154:157], v[172:175], v[26:29]
	v_mfma_i32_16x16x64_i8 v[22:25], v[146:149], v[184:187], v[22:25]
	v_mfma_i32_16x16x64_i8 v[18:21], v[154:157], v[184:187], v[18:21]
	v_mfma_i32_16x16x64_i8 v[6:9], v[146:149], v[192:195], v[6:9]
	v_mfma_i32_16x16x64_i8 v[2:5], v[154:157], v[192:195], v[2:5]
	v_mfma_i32_16x16x64_i8 v[46:49], v[150:153], v[168:171], v[46:49]
	v_mfma_i32_16x16x64_i8 v[42:45], v[160:163], v[168:171], v[42:45]
	v_mfma_i32_16x16x64_i8 v[30:33], v[150:153], v[180:183], v[30:33]
	v_mfma_i32_16x16x64_i8 v[26:29], v[160:163], v[180:183], v[26:29]
	v_mfma_i32_16x16x64_i8 v[22:25], v[150:153], v[188:191], v[22:25]
	v_mfma_i32_16x16x64_i8 v[18:21], v[160:163], v[188:191], v[18:21]
	v_mfma_i32_16x16x64_i8 v[6:9], v[150:153], v[196:199], v[6:9]
	v_mfma_i32_16x16x64_i8 v[2:5], v[160:163], v[196:199], v[2:5]
	s_barrier
	s_add_i32 s29, 0, 0x18000
	s_add_i32 s76, 0, 0x1c000
	v_add_u32_e32 v142, s29, v179
	v_add_u32_e32 v160, s76, v179
	ds_read_b128 v[130:133], v142
	ds_read_b128 v[134:137], v142 offset:1024
	ds_read_b128 v[138:141], v142 offset:2048
	ds_read_b128 v[142:145], v142 offset:3072
	ds_read_b128 v[146:149], v160
	ds_read_b128 v[150:153], v160 offset:1024
	ds_read_b128 v[154:157], v160 offset:2048
	ds_read_b128 v[160:163], v160 offset:3072
	s_add_u32 s46, s46, 0x80000
	s_addc_u32 s47, s47, 0
	ds_read_b128 v[164:167], v200 offset:32768
	ds_read_b128 v[168:171], v200 offset:33792
	ds_read_b128 v[172:175], v200 offset:34816
	ds_read_b128 v[180:183], v200 offset:35840
	ds_read_b128 v[184:187], v200 offset:36864
	ds_read_b128 v[188:191], v200 offset:37888
	ds_read_b128 v[192:195], v200 offset:38912
	ds_read_b128 v[196:199], v200 offset:39936
	s_mov_b32 m0, s51
	v_lshl_add_u64 v[176:177], s[46:47], 0, v[158:159]
	s_add_u32 s46, s46, 0x40000
	s_addc_u32 s47, s47, 0
	global_load_lds_dwordx4 v[176:177], off
	s_mov_b32 m0, s52
	v_lshl_add_u64 v[176:177], s[46:47], 0, v[158:159]
	global_load_lds_dwordx4 v[176:177], off
	s_waitcnt vmcnt(8)
	s_waitcnt lgkmcnt(0)
	s_barrier
	v_mfma_i32_16x16x64_i8 v[126:129], v[130:133], v[164:167], v[126:129]
	v_mfma_i32_16x16x64_i8 v[122:125], v[138:141], v[164:167], v[122:125]
	v_mfma_i32_16x16x64_i8 v[118:121], v[130:133], v[172:175], v[118:121]
	v_mfma_i32_16x16x64_i8 v[114:117], v[138:141], v[172:175], v[114:117]
	v_mfma_i32_16x16x64_i8 v[102:105], v[130:133], v[184:187], v[102:105]
	v_mfma_i32_16x16x64_i8 v[98:101], v[138:141], v[184:187], v[98:101]
	v_mfma_i32_16x16x64_i8 v[86:89], v[130:133], v[192:195], v[86:89]
	v_mfma_i32_16x16x64_i8 v[82:85], v[138:141], v[192:195], v[82:85]
	v_mfma_i32_16x16x64_i8 v[126:129], v[134:137], v[168:171], v[126:129]
	v_mfma_i32_16x16x64_i8 v[122:125], v[142:145], v[168:171], v[122:125]
	v_mfma_i32_16x16x64_i8 v[118:121], v[134:137], v[180:183], v[118:121]
	v_mfma_i32_16x16x64_i8 v[114:117], v[142:145], v[180:183], v[114:117]
	v_mfma_i32_16x16x64_i8 v[102:105], v[134:137], v[188:191], v[102:105]
	v_mfma_i32_16x16x64_i8 v[98:101], v[142:145], v[188:191], v[98:101]
	v_mfma_i32_16x16x64_i8 v[86:89], v[134:137], v[196:199], v[86:89]
	v_mfma_i32_16x16x64_i8 v[82:85], v[142:145], v[196:199], v[82:85]
	v_mfma_i32_16x16x64_i8 v[110:113], v[146:149], v[164:167], v[110:113]
	v_mfma_i32_16x16x64_i8 v[106:109], v[154:157], v[164:167], v[106:109]
	v_mfma_i32_16x16x64_i8 v[94:97], v[146:149], v[172:175], v[94:97]
	v_mfma_i32_16x16x64_i8 v[90:93], v[154:157], v[172:175], v[90:93]
	v_mfma_i32_16x16x64_i8 v[78:81], v[146:149], v[184:187], v[78:81]
	v_mfma_i32_16x16x64_i8 v[74:77], v[154:157], v[184:187], v[74:77]
	v_mfma_i32_16x16x64_i8 v[70:73], v[146:149], v[192:195], v[70:73]
	v_mfma_i32_16x16x64_i8 v[66:69], v[154:157], v[192:195], v[66:69]
	v_mfma_i32_16x16x64_i8 v[110:113], v[150:153], v[168:171], v[110:113]
	v_mfma_i32_16x16x64_i8 v[106:109], v[160:163], v[168:171], v[106:109]
	v_mfma_i32_16x16x64_i8 v[94:97], v[150:153], v[180:183], v[94:97]
	v_mfma_i32_16x16x64_i8 v[90:93], v[160:163], v[180:183], v[90:93]
	v_mfma_i32_16x16x64_i8 v[78:81], v[150:153], v[188:191], v[78:81]
	v_mfma_i32_16x16x64_i8 v[74:77], v[160:163], v[188:191], v[74:77]
	v_mfma_i32_16x16x64_i8 v[70:73], v[150:153], v[196:199], v[70:73]
	v_mfma_i32_16x16x64_i8 v[66:69], v[160:163], v[196:199], v[66:69]
	s_barrier
	s_add_u32 s46, s44, 0x80
	s_addc_u32 s47, s45, 0
	ds_read_b128 v[164:167], v200 offset:49152
	ds_read_b128 v[168:171], v200 offset:50176
	ds_read_b128 v[172:175], v200 offset:51200
	ds_read_b128 v[180:183], v200 offset:52224
	ds_read_b128 v[184:187], v200 offset:53248
	ds_read_b128 v[188:191], v200 offset:54272
	ds_read_b128 v[192:195], v200 offset:55296
	ds_read_b128 v[196:199], v200 offset:56320
	s_add_i32 s29, s29, s48
	v_lshl_add_u64 v[176:177], s[46:47], 0, v[202:203]
	s_mov_b32 m0, s29
	s_add_u32 s46, s46, 0x30000
	global_load_lds_dwordx4 v[176:177], off
	s_addc_u32 s47, s47, 0
	s_add_i32 m0, s29, 0x2000
	s_add_u32 s44, s44, 0x60080
	s_addc_u32 s45, s45, 0
	v_lshl_add_u64 v[176:177], s[46:47], 0, v[202:203]
	global_load_lds_dwordx4 v[176:177], off
	s_add_i32 s29, s76, s48
	v_lshl_add_u64 v[176:177], s[44:45], 0, v[202:203]
	s_add_u32 s44, s44, 0x30000
	s_mov_b32 m0, s29
	s_addc_u32 s45, s45, 0
	global_load_lds_dwordx4 v[176:177], off
	s_add_i32 m0, s29, 0x2000
	v_lshl_add_u64 v[176:177], s[44:45], 0, v[202:203]
	global_load_lds_dwordx4 v[176:177], off
	s_mov_b32 m0, s53
	v_lshl_add_u64 v[176:177], s[10:11], 0, v[158:159]
	s_add_u32 s10, s10, 0x40000
	s_addc_u32 s11, s11, 0
	global_load_lds_dwordx4 v[176:177], off
	s_mov_b32 m0, s54
	v_lshl_add_u64 v[176:177], s[10:11], 0, v[158:159]
	global_load_lds_dwordx4 v[176:177], off
	s_waitcnt vmcnt(8)
	s_waitcnt lgkmcnt(0)
	s_barrier
	v_mfma_i32_16x16x64_i8 v[62:65], v[130:133], v[164:167], v[62:65]
	v_mfma_i32_16x16x64_i8 v[58:61], v[138:141], v[164:167], v[58:61]
	v_mfma_i32_16x16x64_i8 v[54:57], v[130:133], v[172:175], v[54:57]
	v_mfma_i32_16x16x64_i8 v[50:53], v[138:141], v[172:175], v[50:53]
	v_mfma_i32_16x16x64_i8 v[38:41], v[130:133], v[184:187], v[38:41]
	v_mfma_i32_16x16x64_i8 v[34:37], v[138:141], v[184:187], v[34:37]
	v_mfma_i32_16x16x64_i8 v[14:17], v[130:133], v[192:195], v[14:17]
	v_mfma_i32_16x16x64_i8 v[10:13], v[138:141], v[192:195], v[10:13]
	v_mfma_i32_16x16x64_i8 v[62:65], v[134:137], v[168:171], v[62:65]
	v_mfma_i32_16x16x64_i8 v[58:61], v[142:145], v[168:171], v[58:61]
	v_mfma_i32_16x16x64_i8 v[54:57], v[134:137], v[180:183], v[54:57]
	v_mfma_i32_16x16x64_i8 v[50:53], v[142:145], v[180:183], v[50:53]
	v_mfma_i32_16x16x64_i8 v[38:41], v[134:137], v[188:191], v[38:41]
	v_mfma_i32_16x16x64_i8 v[34:37], v[142:145], v[188:191], v[34:37]
	v_mfma_i32_16x16x64_i8 v[14:17], v[134:137], v[196:199], v[14:17]
	v_mfma_i32_16x16x64_i8 v[10:13], v[142:145], v[196:199], v[10:13]
	v_mfma_i32_16x16x64_i8 v[46:49], v[146:149], v[164:167], v[46:49]
	v_mfma_i32_16x16x64_i8 v[42:45], v[154:157], v[164:167], v[42:45]
	v_mfma_i32_16x16x64_i8 v[30:33], v[146:149], v[172:175], v[30:33]
	v_mfma_i32_16x16x64_i8 v[26:29], v[154:157], v[172:175], v[26:29]
	v_mfma_i32_16x16x64_i8 v[22:25], v[146:149], v[184:187], v[22:25]
	v_mfma_i32_16x16x64_i8 v[18:21], v[154:157], v[184:187], v[18:21]
	v_mfma_i32_16x16x64_i8 v[6:9], v[146:149], v[192:195], v[6:9]
	v_mfma_i32_16x16x64_i8 v[2:5], v[154:157], v[192:195], v[2:5]
	v_mfma_i32_16x16x64_i8 v[46:49], v[150:153], v[168:171], v[46:49]
	v_mfma_i32_16x16x64_i8 v[42:45], v[160:163], v[168:171], v[42:45]
	v_mfma_i32_16x16x64_i8 v[30:33], v[150:153], v[180:183], v[30:33]
	v_mfma_i32_16x16x64_i8 v[26:29], v[160:163], v[180:183], v[26:29]
	v_mfma_i32_16x16x64_i8 v[22:25], v[150:153], v[188:191], v[22:25]
	v_mfma_i32_16x16x64_i8 v[18:21], v[160:163], v[188:191], v[18:21]
	v_mfma_i32_16x16x64_i8 v[6:9], v[150:153], v[196:199], v[6:9]
	v_mfma_i32_16x16x64_i8 v[2:5], v[160:163], v[196:199], v[2:5]
	s_barrier
	s_add_u32 s74, s74, 0x100
	s_addc_u32 s75, s75, 0
	s_add_u32 s72, s72, 0x100
	s_addc_u32 s73, s73, 0
	s_cmp_ge_i32 s28, s69
	s_mov_b32 s10, s28
	s_cbranch_scc0 .LBB0_1026
	s_and_b64 vcc, exec, s[18:19]
	s_cbranch_vccz .LBB0_1029
	s_barrier

.Lop_nopf:
	ds_read_b128 v[130:133], v142
	ds_read_b128 v[134:137], v142 offset:1024
	ds_read_b128 v[138:141], v142 offset:2048
	ds_read_b128 v[142:145], v142 offset:3072
	ds_read_b128 v[146:149], v158
	ds_read_b128 v[150:153], v158 offset:1024
	ds_read_b128 v[154:157], v158 offset:2048
	ds_read_b128 v[158:161], v158 offset:3072
	s_mov_b64 s[74:75], s[46:47]
	ds_read_b128 v[162:165], v237
	ds_read_b128 v[166:169], v237 offset:1024
	ds_read_b128 v[170:173], v237 offset:2048
	ds_read_b128 v[174:177], v237 offset:3072
	ds_read_b128 v[178:181], v237 offset:4096
	ds_read_b128 v[182:185], v237 offset:5120
	ds_read_b128 v[188:191], v237 offset:6144
	ds_read_b128 v[192:195], v237 offset:7168
	s_add_i32 m0, s62, 0xc000
	v_lshl_add_u64 v[196:197], s[74:75], 0, v[186:187]
	s_add_u32 s74, s74, 0x40000
	s_addc_u32 s75, s75, 0
	global_load_lds_dwordx4 v[196:197], off
	s_add_i32 m0, s62, 0xe000
	v_lshl_add_u64 v[196:197], s[74:75], 0, v[186:187]
	global_load_lds_dwordx4 v[196:197], off
	s_waitcnt vmcnt(8)
	s_waitcnt lgkmcnt(0)
	s_barrier
	v_mfma_f32_16x16x32_bf16 v[2:5], v[130:133], v[162:165], v[2:5]
	v_mfma_f32_16x16x32_bf16 v[6:9], v[138:141], v[162:165], v[6:9]
	v_mfma_f32_16x16x32_bf16 v[14:17], v[130:133], v[170:173], v[14:17]
	v_mfma_f32_16x16x32_bf16 v[22:25], v[138:141], v[170:173], v[22:25]
	v_mfma_f32_16x16x32_bf16 v[30:33], v[130:133], v[178:181], v[30:33]
	v_mfma_f32_16x16x32_bf16 v[38:41], v[138:141], v[178:181], v[38:41]
	v_mfma_f32_16x16x32_bf16 v[46:49], v[130:133], v[188:191], v[46:49]
	v_mfma_f32_16x16x32_bf16 v[54:57], v[138:141], v[188:191], v[54:57]
	v_mfma_f32_16x16x32_bf16 v[2:5], v[134:137], v[166:169], v[2:5]
	v_mfma_f32_16x16x32_bf16 v[6:9], v[142:145], v[166:169], v[6:9]
	v_mfma_f32_16x16x32_bf16 v[14:17], v[134:137], v[174:177], v[14:17]
	v_mfma_f32_16x16x32_bf16 v[22:25], v[142:145], v[174:177], v[22:25]
	v_mfma_f32_16x16x32_bf16 v[30:33], v[134:137], v[182:185], v[30:33]
	v_mfma_f32_16x16x32_bf16 v[38:41], v[142:145], v[182:185], v[38:41]
	v_mfma_f32_16x16x32_bf16 v[46:49], v[134:137], v[192:195], v[46:49]
	v_mfma_f32_16x16x32_bf16 v[54:57], v[142:145], v[192:195], v[54:57]
	v_mfma_f32_16x16x32_bf16 v[10:13], v[146:149], v[162:165], v[10:13]
	v_mfma_f32_16x16x32_bf16 v[18:21], v[154:157], v[162:165], v[18:21]
	v_mfma_f32_16x16x32_bf16 v[26:29], v[146:149], v[170:173], v[26:29]
	v_mfma_f32_16x16x32_bf16 v[34:37], v[154:157], v[170:173], v[34:37]
	v_mfma_f32_16x16x32_bf16 v[42:45], v[146:149], v[178:181], v[42:45]
	v_mfma_f32_16x16x32_bf16 v[50:53], v[154:157], v[178:181], v[50:53]
	v_mfma_f32_16x16x32_bf16 v[58:61], v[146:149], v[188:191], v[58:61]
	v_mfma_f32_16x16x32_bf16 v[62:65], v[154:157], v[188:191], v[62:65]
	v_mfma_f32_16x16x32_bf16 v[10:13], v[150:153], v[166:169], v[10:13]
	v_mfma_f32_16x16x32_bf16 v[18:21], v[158:161], v[166:169], v[18:21]
	v_mfma_f32_16x16x32_bf16 v[26:29], v[150:153], v[174:177], v[26:29]
	v_mfma_f32_16x16x32_bf16 v[34:37], v[158:161], v[174:177], v[34:37]
	v_mfma_f32_16x16x32_bf16 v[42:45], v[150:153], v[182:185], v[42:45]
	v_mfma_f32_16x16x32_bf16 v[50:53], v[158:161], v[182:185], v[50:53]
	v_mfma_f32_16x16x32_bf16 v[58:61], v[150:153], v[192:195], v[58:61]
	v_mfma_f32_16x16x32_bf16 v[62:65], v[158:161], v[192:195], v[62:65]
	s_barrier
	s_mov_b64 s[74:75], s[54:55]
	ds_read_b128 v[162:165], v237 offset:16384
	ds_read_b128 v[166:169], v237 offset:17408
	ds_read_b128 v[170:173], v237 offset:18432
	ds_read_b128 v[174:177], v237 offset:19456
	ds_read_b128 v[178:181], v237 offset:20480
	ds_read_b128 v[182:185], v237 offset:21504
	ds_read_b128 v[188:191], v237 offset:22528
	ds_read_b128 v[192:195], v237 offset:23552
	s_add_i32 s76, s76, s61
	v_lshl_add_u64 v[196:197], s[74:75], 0, v[202:203]
	s_add_u32 s74, s74, 0x40000
	s_mov_b32 m0, s76
	s_addc_u32 s75, s75, 0
	global_load_lds_dwordx4 v[196:197], off
	s_add_i32 m0, s76, 0x2000
	v_lshl_add_u64 v[196:197], s[74:75], 0, v[202:203]
	s_add_u32 s74, s54, 0x80000
	s_addc_u32 s75, s55, 0
	global_load_lds_dwordx4 v[196:197], off
	s_add_i32 s76, s77, s61
	v_lshl_add_u64 v[196:197], s[74:75], 0, v[202:203]
	s_add_u32 s74, s74, 0x40000
	s_mov_b32 m0, s76
	s_addc_u32 s75, s75, 0
	global_load_lds_dwordx4 v[196:197], off
	s_add_i32 m0, s76, 0x2000
	v_lshl_add_u64 v[196:197], s[74:75], 0, v[202:203]
	s_mov_b64 s[74:75], s[56:57]
	global_load_lds_dwordx4 v[196:197], off
	s_mov_b32 m0, s62
	v_lshl_add_u64 v[196:197], s[74:75], 0, v[186:187]
	s_add_u32 s74, s74, 0x40000
	s_addc_u32 s75, s75, 0
	global_load_lds_dwordx4 v[196:197], off
	s_mov_b32 m0, s63
	v_lshl_add_u64 v[196:197], s[74:75], 0, v[186:187]
	global_load_lds_dwordx4 v[196:197], off
	s_waitcnt vmcnt(8)
	s_waitcnt lgkmcnt(0)
	s_barrier
	v_mfma_f32_16x16x32_bf16 v[66:69], v[130:133], v[162:165], v[66:69]
	v_mfma_f32_16x16x32_bf16 v[70:73], v[138:141], v[162:165], v[70:73]
	v_mfma_f32_16x16x32_bf16 v[74:77], v[130:133], v[170:173], v[74:77]
	v_mfma_f32_16x16x32_bf16 v[78:81], v[138:141], v[170:173], v[78:81]
	v_mfma_f32_16x16x32_bf16 v[86:89], v[130:133], v[178:181], v[86:89]
	v_mfma_f32_16x16x32_bf16 v[94:97], v[138:141], v[178:181], v[94:97]
	v_mfma_f32_16x16x32_bf16 v[102:105], v[130:133], v[188:191], v[102:105]
	v_mfma_f32_16x16x32_bf16 v[110:113], v[138:141], v[188:191], v[110:113]
	v_mfma_f32_16x16x32_bf16 v[66:69], v[134:137], v[166:169], v[66:69]
	v_mfma_f32_16x16x32_bf16 v[70:73], v[142:145], v[166:169], v[70:73]
	v_mfma_f32_16x16x32_bf16 v[74:77], v[134:137], v[174:177], v[74:77]
	v_mfma_f32_16x16x32_bf16 v[78:81], v[142:145], v[174:177], v[78:81]
	v_mfma_f32_16x16x32_bf16 v[86:89], v[134:137], v[182:185], v[86:89]
	v_mfma_f32_16x16x32_bf16 v[94:97], v[142:145], v[182:185], v[94:97]
	v_mfma_f32_16x16x32_bf16 v[102:105], v[134:137], v[192:195], v[102:105]
	v_mfma_f32_16x16x32_bf16 v[110:113], v[142:145], v[192:195], v[110:113]
	v_mfma_f32_16x16x32_bf16 v[82:85], v[146:149], v[162:165], v[82:85]
	v_mfma_f32_16x16x32_bf16 v[90:93], v[154:157], v[162:165], v[90:93]
	v_mfma_f32_16x16x32_bf16 v[98:101], v[146:149], v[170:173], v[98:101]
	v_mfma_f32_16x16x32_bf16 v[106:109], v[154:157], v[170:173], v[106:109]
	v_mfma_f32_16x16x32_bf16 v[114:117], v[146:149], v[178:181], v[114:117]
	v_mfma_f32_16x16x32_bf16 v[118:121], v[154:157], v[178:181], v[118:121]
	v_mfma_f32_16x16x32_bf16 v[122:125], v[146:149], v[188:191], v[122:125]
	v_mfma_f32_16x16x32_bf16 v[126:129], v[154:157], v[188:191], v[126:129]
	v_mfma_f32_16x16x32_bf16 v[82:85], v[150:153], v[166:169], v[82:85]
	v_mfma_f32_16x16x32_bf16 v[90:93], v[158:161], v[166:169], v[90:93]
	v_mfma_f32_16x16x32_bf16 v[98:101], v[150:153], v[174:177], v[98:101]
	v_mfma_f32_16x16x32_bf16 v[106:109], v[158:161], v[174:177], v[106:109]
	v_mfma_f32_16x16x32_bf16 v[114:117], v[150:153], v[182:185], v[114:117]
	v_mfma_f32_16x16x32_bf16 v[118:121], v[158:161], v[182:185], v[118:121]
	v_mfma_f32_16x16x32_bf16 v[122:125], v[150:153], v[192:195], v[122:125]
	v_mfma_f32_16x16x32_bf16 v[126:129], v[158:161], v[192:195], v[126:129]
	s_barrier
	s_add_i32 s74, 0, 0x18000
	s_add_i32 s75, 0, 0x1c000
	v_add_u32_e32 v142, s74, v207
	v_add_u32_e32 v158, s75, v207
	ds_read_b128 v[130:133], v142
	ds_read_b128 v[134:137], v142 offset:1024
	ds_read_b128 v[138:141], v142 offset:2048
	ds_read_b128 v[142:145], v142 offset:3072
	ds_read_b128 v[146:149], v158
	ds_read_b128 v[150:153], v158 offset:1024
	ds_read_b128 v[154:157], v158 offset:2048
	ds_read_b128 v[158:161], v158 offset:3072
	s_add_u32 s56, s56, 0x80000
	s_addc_u32 s57, s57, 0
	ds_read_b128 v[162:165], v237 offset:32768
	ds_read_b128 v[166:169], v237 offset:33792
	ds_read_b128 v[170:173], v237 offset:34816
	ds_read_b128 v[174:177], v237 offset:35840
	ds_read_b128 v[178:181], v237 offset:36864
	ds_read_b128 v[182:185], v237 offset:37888
	ds_read_b128 v[188:191], v237 offset:38912
	ds_read_b128 v[192:195], v237 offset:39936
	s_mov_b32 m0, s64
	v_lshl_add_u64 v[196:197], s[56:57], 0, v[186:187]
	s_add_u32 s56, s56, 0x40000
	s_addc_u32 s57, s57, 0
	global_load_lds_dwordx4 v[196:197], off
	s_mov_b32 m0, s65
	v_lshl_add_u64 v[196:197], s[56:57], 0, v[186:187]
	global_load_lds_dwordx4 v[196:197], off
	s_waitcnt vmcnt(8)
	s_waitcnt lgkmcnt(0)
	s_barrier
	v_mfma_f32_16x16x32_bf16 v[2:5], v[130:133], v[162:165], v[2:5]
	v_mfma_f32_16x16x32_bf16 v[6:9], v[138:141], v[162:165], v[6:9]
	v_mfma_f32_16x16x32_bf16 v[14:17], v[130:133], v[170:173], v[14:17]
	v_mfma_f32_16x16x32_bf16 v[22:25], v[138:141], v[170:173], v[22:25]
	v_mfma_f32_16x16x32_bf16 v[30:33], v[130:133], v[178:181], v[30:33]
	v_mfma_f32_16x16x32_bf16 v[38:41], v[138:141], v[178:181], v[38:41]
	v_mfma_f32_16x16x32_bf16 v[46:49], v[130:133], v[188:191], v[46:49]
	v_mfma_f32_16x16x32_bf16 v[54:57], v[138:141], v[188:191], v[54:57]
	v_mfma_f32_16x16x32_bf16 v[2:5], v[134:137], v[166:169], v[2:5]
	v_mfma_f32_16x16x32_bf16 v[6:9], v[142:145], v[166:169], v[6:9]
	v_mfma_f32_16x16x32_bf16 v[14:17], v[134:137], v[174:177], v[14:17]
	v_mfma_f32_16x16x32_bf16 v[22:25], v[142:145], v[174:177], v[22:25]
	v_mfma_f32_16x16x32_bf16 v[30:33], v[134:137], v[182:185], v[30:33]
	v_mfma_f32_16x16x32_bf16 v[38:41], v[142:145], v[182:185], v[38:41]
	v_mfma_f32_16x16x32_bf16 v[46:49], v[134:137], v[192:195], v[46:49]
	v_mfma_f32_16x16x32_bf16 v[54:57], v[142:145], v[192:195], v[54:57]
	v_mfma_f32_16x16x32_bf16 v[10:13], v[146:149], v[162:165], v[10:13]
	v_mfma_f32_16x16x32_bf16 v[18:21], v[154:157], v[162:165], v[18:21]
	v_mfma_f32_16x16x32_bf16 v[26:29], v[146:149], v[170:173], v[26:29]
	v_mfma_f32_16x16x32_bf16 v[34:37], v[154:157], v[170:173], v[34:37]
	v_mfma_f32_16x16x32_bf16 v[42:45], v[146:149], v[178:181], v[42:45]
	v_mfma_f32_16x16x32_bf16 v[50:53], v[154:157], v[178:181], v[50:53]
	v_mfma_f32_16x16x32_bf16 v[58:61], v[146:149], v[188:191], v[58:61]
	v_mfma_f32_16x16x32_bf16 v[62:65], v[154:157], v[188:191], v[62:65]
	v_mfma_f32_16x16x32_bf16 v[10:13], v[150:153], v[166:169], v[10:13]
	v_mfma_f32_16x16x32_bf16 v[18:21], v[158:161], v[166:169], v[18:21]
	v_mfma_f32_16x16x32_bf16 v[26:29], v[150:153], v[174:177], v[26:29]
	v_mfma_f32_16x16x32_bf16 v[34:37], v[158:161], v[174:177], v[34:37]
	v_mfma_f32_16x16x32_bf16 v[42:45], v[150:153], v[182:185], v[42:45]
	v_mfma_f32_16x16x32_bf16 v[50:53], v[158:161], v[182:185], v[50:53]
	v_mfma_f32_16x16x32_bf16 v[58:61], v[150:153], v[192:195], v[58:61]
	v_mfma_f32_16x16x32_bf16 v[62:65], v[158:161], v[192:195], v[62:65]
	s_barrier
	s_add_u32 s56, s54, 0x80
	s_addc_u32 s57, s55, 0
	ds_read_b128 v[162:165], v237 offset:49152
	ds_read_b128 v[166:169], v237 offset:50176
	ds_read_b128 v[170:173], v237 offset:51200
	ds_read_b128 v[174:177], v237 offset:52224
	ds_read_b128 v[178:181], v237 offset:53248
	ds_read_b128 v[182:185], v237 offset:54272
	ds_read_b128 v[188:191], v237 offset:55296
	ds_read_b128 v[192:195], v237 offset:56320
	s_add_i32 s74, s74, s61
	v_lshl_add_u64 v[196:197], s[56:57], 0, v[202:203]
	s_mov_b32 m0, s74
	s_add_u32 s56, s56, 0x40000
	global_load_lds_dwordx4 v[196:197], off
	s_addc_u32 s57, s57, 0
	s_add_i32 m0, s74, 0x2000
	s_add_u32 s54, s54, 0x80080
	s_addc_u32 s55, s55, 0
	v_lshl_add_u64 v[196:197], s[56:57], 0, v[202:203]
	global_load_lds_dwordx4 v[196:197], off
	s_add_i32 s56, s75, s61
	v_lshl_add_u64 v[196:197], s[54:55], 0, v[202:203]
	s_add_u32 s54, s54, 0x40000
	s_mov_b32 m0, s56
	s_addc_u32 s55, s55, 0
	global_load_lds_dwordx4 v[196:197], off
	s_add_i32 m0, s56, 0x2000
	v_lshl_add_u64 v[196:197], s[54:55], 0, v[202:203]
	global_load_lds_dwordx4 v[196:197], off
	s_mov_b32 m0, s66
	v_lshl_add_u64 v[196:197], s[48:49], 0, v[186:187]
	s_add_u32 s48, s48, 0x40000
	s_addc_u32 s49, s49, 0
	global_load_lds_dwordx4 v[196:197], off
	s_mov_b32 m0, s67
	v_lshl_add_u64 v[196:197], s[48:49], 0, v[186:187]
	global_load_lds_dwordx4 v[196:197], off
	s_waitcnt vmcnt(8)
	s_waitcnt lgkmcnt(0)
	s_barrier
	v_mfma_f32_16x16x32_bf16 v[66:69], v[130:133], v[162:165], v[66:69]
	v_mfma_f32_16x16x32_bf16 v[70:73], v[138:141], v[162:165], v[70:73]
	v_mfma_f32_16x16x32_bf16 v[74:77], v[130:133], v[170:173], v[74:77]
	v_mfma_f32_16x16x32_bf16 v[78:81], v[138:141], v[170:173], v[78:81]
	v_mfma_f32_16x16x32_bf16 v[86:89], v[130:133], v[178:181], v[86:89]
	v_mfma_f32_16x16x32_bf16 v[94:97], v[138:141], v[178:181], v[94:97]
	v_mfma_f32_16x16x32_bf16 v[102:105], v[130:133], v[188:191], v[102:105]
	v_mfma_f32_16x16x32_bf16 v[110:113], v[138:141], v[188:191], v[110:113]
	v_mfma_f32_16x16x32_bf16 v[66:69], v[134:137], v[166:169], v[66:69]
	v_mfma_f32_16x16x32_bf16 v[70:73], v[142:145], v[166:169], v[70:73]
	v_mfma_f32_16x16x32_bf16 v[74:77], v[134:137], v[174:177], v[74:77]
	v_mfma_f32_16x16x32_bf16 v[78:81], v[142:145], v[174:177], v[78:81]
	v_mfma_f32_16x16x32_bf16 v[86:89], v[134:137], v[182:185], v[86:89]
	v_mfma_f32_16x16x32_bf16 v[94:97], v[142:145], v[182:185], v[94:97]
	v_mfma_f32_16x16x32_bf16 v[102:105], v[134:137], v[192:195], v[102:105]
	v_mfma_f32_16x16x32_bf16 v[110:113], v[142:145], v[192:195], v[110:113]
	v_mfma_f32_16x16x32_bf16 v[82:85], v[146:149], v[162:165], v[82:85]
	v_mfma_f32_16x16x32_bf16 v[90:93], v[154:157], v[162:165], v[90:93]
	v_mfma_f32_16x16x32_bf16 v[98:101], v[146:149], v[170:173], v[98:101]
	v_mfma_f32_16x16x32_bf16 v[106:109], v[154:157], v[170:173], v[106:109]
	v_mfma_f32_16x16x32_bf16 v[114:117], v[146:149], v[178:181], v[114:117]
	v_mfma_f32_16x16x32_bf16 v[118:121], v[154:157], v[178:181], v[118:121]
	v_mfma_f32_16x16x32_bf16 v[122:125], v[146:149], v[188:191], v[122:125]
	v_mfma_f32_16x16x32_bf16 v[126:129], v[154:157], v[188:191], v[126:129]
	v_mfma_f32_16x16x32_bf16 v[82:85], v[150:153], v[166:169], v[82:85]
	v_mfma_f32_16x16x32_bf16 v[90:93], v[158:161], v[166:169], v[90:93]
	v_mfma_f32_16x16x32_bf16 v[98:101], v[150:153], v[174:177], v[98:101]
	v_mfma_f32_16x16x32_bf16 v[106:109], v[158:161], v[174:177], v[106:109]
	v_mfma_f32_16x16x32_bf16 v[114:117], v[150:153], v[182:185], v[114:117]
	v_mfma_f32_16x16x32_bf16 v[118:121], v[158:161], v[182:185], v[118:121]
	v_mfma_f32_16x16x32_bf16 v[122:125], v[150:153], v[192:195], v[122:125]
	v_mfma_f32_16x16x32_bf16 v[126:129], v[158:161], v[192:195], v[126:129]
	s_barrier
	s_add_i32 s29, s29, 2
	s_add_u32 s7, s7, 0x100
	s_addc_u32 s21, s21, 0
	s_add_u32 s27, s27, 0x100
	s_addc_u32 s28, s28, 0
	s_add_u32 s46, s46, 0x100
	s_addc_u32 s47, s47, 0
	s_cmp_gt_u32 s29, 29
	s_cbranch_scc0 .LBB0_1096
	s_and_b64 vcc, exec, s[18:19]
	s_cbranch_vccz .LBB0_1099
	s_barrier

.Lfu_nopf:
	s_add_u32 s46, s50, 0x80
	s_addc_u32 s47, s51, 0
	s_add_i32 s68, 0, 0x10000
	s_add_i32 s69, 0, 0x14000
	v_add_u32_e32 v142, s68, v208
	v_add_u32_e32 v158, s69, v208
	ds_read_b128 v[130:133], v142
	ds_read_b128 v[134:137], v142 offset:1024
	ds_read_b128 v[138:141], v142 offset:2048
	ds_read_b128 v[142:145], v142 offset:3072
	ds_read_b128 v[146:149], v158
	ds_read_b128 v[150:153], v158 offset:1024
	ds_read_b128 v[154:157], v158 offset:2048
	ds_read_b128 v[158:161], v158 offset:3072
	s_add_u32 s66, s23, 0x7ff80
	s_addc_u32 s67, s62, 0
	ds_read_b128 v[162:165], v210
	ds_read_b128 v[166:169], v210 offset:1024
	ds_read_b128 v[170:173], v210 offset:2048
	ds_read_b128 v[174:177], v210 offset:3072
	ds_read_b128 v[180:183], v210 offset:4096
	ds_read_b128 v[184:187], v210 offset:5120
	ds_read_b128 v[188:191], v210 offset:6144
	ds_read_b128 v[192:195], v210 offset:7168
	s_add_i32 m0, s52, 0xc000
	v_lshl_add_u64 v[196:197], s[66:67], 0, v[178:179]
	s_add_u32 s66, s66, 0x40000
	s_addc_u32 s67, s67, 0
	global_load_lds_dwordx4 v[196:197], off
	s_add_i32 m0, s52, 0xe000
	v_lshl_add_u64 v[196:197], s[66:67], 0, v[178:179]
	global_load_lds_dwordx4 v[196:197], off
	s_waitcnt vmcnt(8)
	s_waitcnt lgkmcnt(0)
	s_barrier
	v_mfma_i32_16x16x64_i8 v[126:129], v[130:133], v[162:165], v[126:129]
	v_mfma_i32_16x16x64_i8 v[118:121], v[138:141], v[162:165], v[118:121]
	v_mfma_i32_16x16x64_i8 v[110:113], v[130:133], v[170:173], v[110:113]
	v_mfma_i32_16x16x64_i8 v[102:105], v[138:141], v[170:173], v[102:105]
	v_mfma_i32_16x16x64_i8 v[94:97], v[130:133], v[180:183], v[94:97]
	v_mfma_i32_16x16x64_i8 v[86:89], v[138:141], v[180:183], v[86:89]
	v_mfma_i32_16x16x64_i8 v[78:81], v[130:133], v[188:191], v[78:81]
	v_mfma_i32_16x16x64_i8 v[70:73], v[138:141], v[188:191], v[70:73]
	v_mfma_i32_16x16x64_i8 v[126:129], v[134:137], v[166:169], v[126:129]
	v_mfma_i32_16x16x64_i8 v[118:121], v[142:145], v[166:169], v[118:121]
	v_mfma_i32_16x16x64_i8 v[110:113], v[134:137], v[174:177], v[110:113]
	v_mfma_i32_16x16x64_i8 v[102:105], v[142:145], v[174:177], v[102:105]
	v_mfma_i32_16x16x64_i8 v[94:97], v[134:137], v[184:187], v[94:97]
	v_mfma_i32_16x16x64_i8 v[86:89], v[142:145], v[184:187], v[86:89]
	v_mfma_i32_16x16x64_i8 v[78:81], v[134:137], v[192:195], v[78:81]
	v_mfma_i32_16x16x64_i8 v[70:73], v[142:145], v[192:195], v[70:73]
	v_mfma_i32_16x16x64_i8 v[122:125], v[146:149], v[162:165], v[122:125]
	v_mfma_i32_16x16x64_i8 v[114:117], v[154:157], v[162:165], v[114:117]
	v_mfma_i32_16x16x64_i8 v[106:109], v[146:149], v[170:173], v[106:109]
	v_mfma_i32_16x16x64_i8 v[98:101], v[154:157], v[170:173], v[98:101]
	v_mfma_i32_16x16x64_i8 v[90:93], v[146:149], v[180:183], v[90:93]
	v_mfma_i32_16x16x64_i8 v[82:85], v[154:157], v[180:183], v[82:85]
	v_mfma_i32_16x16x64_i8 v[74:77], v[146:149], v[188:191], v[74:77]
	v_mfma_i32_16x16x64_i8 v[66:69], v[154:157], v[188:191], v[66:69]
	v_mfma_i32_16x16x64_i8 v[122:125], v[150:153], v[166:169], v[122:125]
	v_mfma_i32_16x16x64_i8 v[114:117], v[158:161], v[166:169], v[114:117]
	v_mfma_i32_16x16x64_i8 v[106:109], v[150:153], v[174:177], v[106:109]
	v_mfma_i32_16x16x64_i8 v[98:101], v[158:161], v[174:177], v[98:101]
	v_mfma_i32_16x16x64_i8 v[90:93], v[150:153], v[184:187], v[90:93]
	v_mfma_i32_16x16x64_i8 v[82:85], v[158:161], v[184:187], v[82:85]
	v_mfma_i32_16x16x64_i8 v[74:77], v[150:153], v[192:195], v[74:77]
	v_mfma_i32_16x16x64_i8 v[66:69], v[158:161], v[192:195], v[66:69]
	s_barrier
	s_mov_b64 s[66:67], s[48:49]
	ds_read_b128 v[162:165], v210 offset:16384
	ds_read_b128 v[166:169], v210 offset:17408
	ds_read_b128 v[170:173], v210 offset:18432
	ds_read_b128 v[174:177], v210 offset:19456
	ds_read_b128 v[180:183], v210 offset:20480
	ds_read_b128 v[184:187], v210 offset:21504
	ds_read_b128 v[188:191], v210 offset:22528
	ds_read_b128 v[192:195], v210 offset:23552
	s_add_i32 s68, s68, s31
	v_lshl_add_u64 v[196:197], s[66:67], 0, v[202:203]
	s_add_u32 s66, s66, 0x20000
	s_mov_b32 m0, s68
	s_addc_u32 s67, s67, 0
	global_load_lds_dwordx4 v[196:197], off
	s_add_i32 m0, s68, 0x2000
	v_lshl_add_u64 v[196:197], s[66:67], 0, v[202:203]
	s_add_u32 s66, s48, 0x40000
	s_addc_u32 s67, s49, 0
	global_load_lds_dwordx4 v[196:197], off
	s_add_i32 s68, s69, s31
	v_lshl_add_u64 v[196:197], s[66:67], 0, v[202:203]
	s_add_u32 s66, s66, 0x20000
	s_mov_b32 m0, s68
	s_addc_u32 s67, s67, 0
	global_load_lds_dwordx4 v[196:197], off
	s_add_i32 m0, s68, 0x2000
	v_lshl_add_u64 v[196:197], s[66:67], 0, v[202:203]
	s_mov_b64 s[66:67], s[50:51]
	global_load_lds_dwordx4 v[196:197], off
	s_mov_b32 m0, s52
	v_lshl_add_u64 v[196:197], s[66:67], 0, v[178:179]
	s_add_u32 s66, s66, 0x40000
	s_addc_u32 s67, s67, 0
	global_load_lds_dwordx4 v[196:197], off
	s_mov_b32 m0, s53
	v_lshl_add_u64 v[196:197], s[66:67], 0, v[178:179]
	global_load_lds_dwordx4 v[196:197], off
	s_waitcnt vmcnt(8)
	s_waitcnt lgkmcnt(0)
	s_barrier
	v_mfma_i32_16x16x64_i8 v[62:65], v[130:133], v[162:165], v[62:65]
	v_mfma_i32_16x16x64_i8 v[54:57], v[138:141], v[162:165], v[54:57]
	v_mfma_i32_16x16x64_i8 v[46:49], v[130:133], v[170:173], v[46:49]
	v_mfma_i32_16x16x64_i8 v[38:41], v[138:141], v[170:173], v[38:41]
	v_mfma_i32_16x16x64_i8 v[30:33], v[130:133], v[180:183], v[30:33]
	v_mfma_i32_16x16x64_i8 v[22:25], v[138:141], v[180:183], v[22:25]
	v_mfma_i32_16x16x64_i8 v[14:17], v[130:133], v[188:191], v[14:17]
	v_mfma_i32_16x16x64_i8 v[6:9], v[138:141], v[188:191], v[6:9]
	v_mfma_i32_16x16x64_i8 v[62:65], v[134:137], v[166:169], v[62:65]
	v_mfma_i32_16x16x64_i8 v[54:57], v[142:145], v[166:169], v[54:57]
	v_mfma_i32_16x16x64_i8 v[46:49], v[134:137], v[174:177], v[46:49]
	v_mfma_i32_16x16x64_i8 v[38:41], v[142:145], v[174:177], v[38:41]
	v_mfma_i32_16x16x64_i8 v[30:33], v[134:137], v[184:187], v[30:33]
	v_mfma_i32_16x16x64_i8 v[22:25], v[142:145], v[184:187], v[22:25]
	v_mfma_i32_16x16x64_i8 v[14:17], v[134:137], v[192:195], v[14:17]
	v_mfma_i32_16x16x64_i8 v[6:9], v[142:145], v[192:195], v[6:9]
	v_mfma_i32_16x16x64_i8 v[58:61], v[146:149], v[162:165], v[58:61]
	v_mfma_i32_16x16x64_i8 v[50:53], v[154:157], v[162:165], v[50:53]
	v_mfma_i32_16x16x64_i8 v[42:45], v[146:149], v[170:173], v[42:45]
	v_mfma_i32_16x16x64_i8 v[34:37], v[154:157], v[170:173], v[34:37]
	v_mfma_i32_16x16x64_i8 v[26:29], v[146:149], v[180:183], v[26:29]
	v_mfma_i32_16x16x64_i8 v[18:21], v[154:157], v[180:183], v[18:21]
	v_mfma_i32_16x16x64_i8 v[10:13], v[146:149], v[188:191], v[10:13]
	v_mfma_i32_16x16x64_i8 v[2:5], v[154:157], v[188:191], v[2:5]
	v_mfma_i32_16x16x64_i8 v[58:61], v[150:153], v[166:169], v[58:61]
	v_mfma_i32_16x16x64_i8 v[50:53], v[158:161], v[166:169], v[50:53]
	v_mfma_i32_16x16x64_i8 v[42:45], v[150:153], v[174:177], v[42:45]
	v_mfma_i32_16x16x64_i8 v[34:37], v[158:161], v[174:177], v[34:37]
	v_mfma_i32_16x16x64_i8 v[26:29], v[150:153], v[184:187], v[26:29]
	v_mfma_i32_16x16x64_i8 v[18:21], v[158:161], v[184:187], v[18:21]
	v_mfma_i32_16x16x64_i8 v[10:13], v[150:153], v[192:195], v[10:13]
	v_mfma_i32_16x16x64_i8 v[2:5], v[158:161], v[192:195], v[2:5]
	s_barrier
	s_add_i32 s66, 0, 0x18000
	s_add_i32 s67, 0, 0x1c000
	v_add_u32_e32 v142, s66, v208
	v_add_u32_e32 v158, s67, v208
	ds_read_b128 v[130:133], v142
	ds_read_b128 v[134:137], v142 offset:1024
	ds_read_b128 v[138:141], v142 offset:2048
	ds_read_b128 v[142:145], v142 offset:3072
	ds_read_b128 v[146:149], v158
	ds_read_b128 v[150:153], v158 offset:1024
	ds_read_b128 v[154:157], v158 offset:2048
	ds_read_b128 v[158:161], v158 offset:3072
	s_add_u32 s50, s50, 0x80000
	s_addc_u32 s51, s51, 0
	ds_read_b128 v[162:165], v210 offset:32768
	ds_read_b128 v[166:169], v210 offset:33792
	ds_read_b128 v[170:173], v210 offset:34816
	ds_read_b128 v[174:177], v210 offset:35840
	ds_read_b128 v[180:183], v210 offset:36864
	ds_read_b128 v[184:187], v210 offset:37888
	ds_read_b128 v[188:191], v210 offset:38912
	ds_read_b128 v[192:195], v210 offset:39936
	s_mov_b32 m0, s54
	v_lshl_add_u64 v[196:197], s[50:51], 0, v[178:179]
	s_add_u32 s50, s50, 0x40000
	s_addc_u32 s51, s51, 0
	global_load_lds_dwordx4 v[196:197], off
	s_mov_b32 m0, s55
	v_lshl_add_u64 v[196:197], s[50:51], 0, v[178:179]
	global_load_lds_dwordx4 v[196:197], off
	s_waitcnt vmcnt(8)
	s_waitcnt lgkmcnt(0)
	s_barrier
	v_mfma_i32_16x16x64_i8 v[126:129], v[130:133], v[162:165], v[126:129]
	v_mfma_i32_16x16x64_i8 v[118:121], v[138:141], v[162:165], v[118:121]
	v_mfma_i32_16x16x64_i8 v[110:113], v[130:133], v[170:173], v[110:113]
	v_mfma_i32_16x16x64_i8 v[102:105], v[138:141], v[170:173], v[102:105]
	v_mfma_i32_16x16x64_i8 v[94:97], v[130:133], v[180:183], v[94:97]
	v_mfma_i32_16x16x64_i8 v[86:89], v[138:141], v[180:183], v[86:89]
	v_mfma_i32_16x16x64_i8 v[78:81], v[130:133], v[188:191], v[78:81]
	v_mfma_i32_16x16x64_i8 v[70:73], v[138:141], v[188:191], v[70:73]
	v_mfma_i32_16x16x64_i8 v[126:129], v[134:137], v[166:169], v[126:129]
	v_mfma_i32_16x16x64_i8 v[118:121], v[142:145], v[166:169], v[118:121]
	v_mfma_i32_16x16x64_i8 v[110:113], v[134:137], v[174:177], v[110:113]
	v_mfma_i32_16x16x64_i8 v[102:105], v[142:145], v[174:177], v[102:105]
	v_mfma_i32_16x16x64_i8 v[94:97], v[134:137], v[184:187], v[94:97]
	v_mfma_i32_16x16x64_i8 v[86:89], v[142:145], v[184:187], v[86:89]
	v_mfma_i32_16x16x64_i8 v[78:81], v[134:137], v[192:195], v[78:81]
	v_mfma_i32_16x16x64_i8 v[70:73], v[142:145], v[192:195], v[70:73]
	v_mfma_i32_16x16x64_i8 v[122:125], v[146:149], v[162:165], v[122:125]
	v_mfma_i32_16x16x64_i8 v[114:117], v[154:157], v[162:165], v[114:117]
	v_mfma_i32_16x16x64_i8 v[106:109], v[146:149], v[170:173], v[106:109]
	v_mfma_i32_16x16x64_i8 v[98:101], v[154:157], v[170:173], v[98:101]
	v_mfma_i32_16x16x64_i8 v[90:93], v[146:149], v[180:183], v[90:93]
	v_mfma_i32_16x16x64_i8 v[82:85], v[154:157], v[180:183], v[82:85]
	v_mfma_i32_16x16x64_i8 v[74:77], v[146:149], v[188:191], v[74:77]
	v_mfma_i32_16x16x64_i8 v[66:69], v[154:157], v[188:191], v[66:69]
	v_mfma_i32_16x16x64_i8 v[122:125], v[150:153], v[166:169], v[122:125]
	v_mfma_i32_16x16x64_i8 v[114:117], v[158:161], v[166:169], v[114:117]
	v_mfma_i32_16x16x64_i8 v[106:109], v[150:153], v[174:177], v[106:109]
	v_mfma_i32_16x16x64_i8 v[98:101], v[158:161], v[174:177], v[98:101]
	v_mfma_i32_16x16x64_i8 v[90:93], v[150:153], v[184:187], v[90:93]
	v_mfma_i32_16x16x64_i8 v[82:85], v[158:161], v[184:187], v[82:85]
	v_mfma_i32_16x16x64_i8 v[74:77], v[150:153], v[192:195], v[74:77]
	v_mfma_i32_16x16x64_i8 v[66:69], v[158:161], v[192:195], v[66:69]
	s_barrier
	s_add_u32 s50, s48, 0x80
	s_addc_u32 s51, s49, 0
	ds_read_b128 v[162:165], v210 offset:49152
	ds_read_b128 v[166:169], v210 offset:50176
	ds_read_b128 v[170:173], v210 offset:51200
	ds_read_b128 v[174:177], v210 offset:52224
	ds_read_b128 v[180:183], v210 offset:53248
	ds_read_b128 v[184:187], v210 offset:54272
	ds_read_b128 v[188:191], v210 offset:55296
	ds_read_b128 v[192:195], v210 offset:56320
	s_add_i32 s66, s66, s31
	v_lshl_add_u64 v[196:197], s[50:51], 0, v[202:203]
	s_mov_b32 m0, s66
	s_add_u32 s50, s50, 0x20000
	global_load_lds_dwordx4 v[196:197], off
	s_addc_u32 s51, s51, 0
	s_add_i32 m0, s66, 0x2000
	s_add_u32 s48, s48, 0x40080
	s_addc_u32 s49, s49, 0
	v_lshl_add_u64 v[196:197], s[50:51], 0, v[202:203]
	global_load_lds_dwordx4 v[196:197], off
	s_add_i32 s50, s67, s31
	v_lshl_add_u64 v[196:197], s[48:49], 0, v[202:203]
	s_add_u32 s48, s48, 0x20000
	s_mov_b32 m0, s50
	s_addc_u32 s49, s49, 0
	global_load_lds_dwordx4 v[196:197], off
	s_add_i32 m0, s50, 0x2000
	v_lshl_add_u64 v[196:197], s[48:49], 0, v[202:203]
	global_load_lds_dwordx4 v[196:197], off
	s_mov_b32 m0, s56
	v_lshl_add_u64 v[196:197], s[46:47], 0, v[178:179]
	s_add_u32 s46, s46, 0x40000
	s_addc_u32 s47, s47, 0
	global_load_lds_dwordx4 v[196:197], off
	s_mov_b32 m0, s57
	v_lshl_add_u64 v[196:197], s[46:47], 0, v[178:179]
	global_load_lds_dwordx4 v[196:197], off
	s_waitcnt vmcnt(8)
	s_waitcnt lgkmcnt(0)
	s_barrier
	v_mfma_i32_16x16x64_i8 v[62:65], v[130:133], v[162:165], v[62:65]
	v_mfma_i32_16x16x64_i8 v[54:57], v[138:141], v[162:165], v[54:57]
	v_mfma_i32_16x16x64_i8 v[46:49], v[130:133], v[170:173], v[46:49]
	v_mfma_i32_16x16x64_i8 v[38:41], v[138:141], v[170:173], v[38:41]
	v_mfma_i32_16x16x64_i8 v[30:33], v[130:133], v[180:183], v[30:33]
	v_mfma_i32_16x16x64_i8 v[22:25], v[138:141], v[180:183], v[22:25]
	v_mfma_i32_16x16x64_i8 v[14:17], v[130:133], v[188:191], v[14:17]
	v_mfma_i32_16x16x64_i8 v[6:9], v[138:141], v[188:191], v[6:9]
	v_mfma_i32_16x16x64_i8 v[62:65], v[134:137], v[166:169], v[62:65]
	v_mfma_i32_16x16x64_i8 v[54:57], v[142:145], v[166:169], v[54:57]
	v_mfma_i32_16x16x64_i8 v[46:49], v[134:137], v[174:177], v[46:49]
	v_mfma_i32_16x16x64_i8 v[38:41], v[142:145], v[174:177], v[38:41]
	v_mfma_i32_16x16x64_i8 v[30:33], v[134:137], v[184:187], v[30:33]
	v_mfma_i32_16x16x64_i8 v[22:25], v[142:145], v[184:187], v[22:25]
	v_mfma_i32_16x16x64_i8 v[14:17], v[134:137], v[192:195], v[14:17]
	v_mfma_i32_16x16x64_i8 v[6:9], v[142:145], v[192:195], v[6:9]
	v_mfma_i32_16x16x64_i8 v[58:61], v[146:149], v[162:165], v[58:61]
	v_mfma_i32_16x16x64_i8 v[50:53], v[154:157], v[162:165], v[50:53]
	v_mfma_i32_16x16x64_i8 v[42:45], v[146:149], v[170:173], v[42:45]
	v_mfma_i32_16x16x64_i8 v[34:37], v[154:157], v[170:173], v[34:37]
	v_mfma_i32_16x16x64_i8 v[26:29], v[146:149], v[180:183], v[26:29]
	v_mfma_i32_16x16x64_i8 v[18:21], v[154:157], v[180:183], v[18:21]
	v_mfma_i32_16x16x64_i8 v[10:13], v[146:149], v[188:191], v[10:13]
	v_mfma_i32_16x16x64_i8 v[2:5], v[154:157], v[188:191], v[2:5]
	v_mfma_i32_16x16x64_i8 v[58:61], v[150:153], v[166:169], v[58:61]
	v_mfma_i32_16x16x64_i8 v[50:53], v[158:161], v[166:169], v[50:53]
	v_mfma_i32_16x16x64_i8 v[42:45], v[150:153], v[174:177], v[42:45]
	v_mfma_i32_16x16x64_i8 v[34:37], v[158:161], v[174:177], v[34:37]
	v_mfma_i32_16x16x64_i8 v[26:29], v[150:153], v[184:187], v[26:29]
	v_mfma_i32_16x16x64_i8 v[18:21], v[158:161], v[184:187], v[18:21]
	v_mfma_i32_16x16x64_i8 v[10:13], v[150:153], v[192:195], v[10:13]
	v_mfma_i32_16x16x64_i8 v[2:5], v[158:161], v[192:195], v[2:5]
	s_barrier
	s_add_i32 s65, s65, 2
	s_add_u32 s23, s23, 0x100
	s_addc_u32 s62, s62, 0
	s_add_u32 s63, s63, 0x100
	s_addc_u32 s64, s64, 0
	s_cmp_gt_u32 s65, 13
	s_cbranch_scc0 .LBB0_1214
	s_and_b64 vcc, exec, s[18:19]
	s_cbranch_vccz .LBB0_1217
	s_barrier

.Lfd_nopf:
	ds_read_b128 v[130:133], v142
	ds_read_b128 v[134:137], v142 offset:1024
	ds_read_b128 v[138:141], v142 offset:2048
	ds_read_b128 v[142:145], v142 offset:3072
	ds_read_b128 v[146:149], v158
	ds_read_b128 v[150:153], v158 offset:1024
	ds_read_b128 v[154:157], v158 offset:2048
	ds_read_b128 v[158:161], v158 offset:3072
	s_mov_b64 s[72:73], s[44:45]
	ds_read_b128 v[162:165], v237
	ds_read_b128 v[166:169], v237 offset:1024
	ds_read_b128 v[170:173], v237 offset:2048
	ds_read_b128 v[174:177], v237 offset:3072
	ds_read_b128 v[178:181], v237 offset:4096
	ds_read_b128 v[182:185], v237 offset:5120
	ds_read_b128 v[188:191], v237 offset:6144
	ds_read_b128 v[192:195], v237 offset:7168
	s_add_i32 m0, s58, 0xc000
	v_lshl_add_u64 v[196:197], s[72:73], 0, v[186:187]
	s_add_u32 s72, s72, 0xb0000
	s_addc_u32 s73, s73, 0
	global_load_lds_dwordx4 v[196:197], off
	s_add_i32 m0, s58, 0xe000
	v_lshl_add_u64 v[196:197], s[72:73], 0, v[186:187]
	global_load_lds_dwordx4 v[196:197], off
	s_waitcnt vmcnt(8)
	s_waitcnt lgkmcnt(0)
	s_barrier
	v_mfma_f32_16x16x32_bf16 v[2:5], v[130:133], v[162:165], v[2:5]
	v_mfma_f32_16x16x32_bf16 v[6:9], v[138:141], v[162:165], v[6:9]
	v_mfma_f32_16x16x32_bf16 v[14:17], v[130:133], v[170:173], v[14:17]
	v_mfma_f32_16x16x32_bf16 v[22:25], v[138:141], v[170:173], v[22:25]
	v_mfma_f32_16x16x32_bf16 v[30:33], v[130:133], v[178:181], v[30:33]
	v_mfma_f32_16x16x32_bf16 v[38:41], v[138:141], v[178:181], v[38:41]
	v_mfma_f32_16x16x32_bf16 v[46:49], v[130:133], v[188:191], v[46:49]
	v_mfma_f32_16x16x32_bf16 v[54:57], v[138:141], v[188:191], v[54:57]
	v_mfma_f32_16x16x32_bf16 v[2:5], v[134:137], v[166:169], v[2:5]
	v_mfma_f32_16x16x32_bf16 v[6:9], v[142:145], v[166:169], v[6:9]
	v_mfma_f32_16x16x32_bf16 v[14:17], v[134:137], v[174:177], v[14:17]
	v_mfma_f32_16x16x32_bf16 v[22:25], v[142:145], v[174:177], v[22:25]
	v_mfma_f32_16x16x32_bf16 v[30:33], v[134:137], v[182:185], v[30:33]
	v_mfma_f32_16x16x32_bf16 v[38:41], v[142:145], v[182:185], v[38:41]
	v_mfma_f32_16x16x32_bf16 v[46:49], v[134:137], v[192:195], v[46:49]
	v_mfma_f32_16x16x32_bf16 v[54:57], v[142:145], v[192:195], v[54:57]
	v_mfma_f32_16x16x32_bf16 v[10:13], v[146:149], v[162:165], v[10:13]
	v_mfma_f32_16x16x32_bf16 v[18:21], v[154:157], v[162:165], v[18:21]
	v_mfma_f32_16x16x32_bf16 v[26:29], v[146:149], v[170:173], v[26:29]
	v_mfma_f32_16x16x32_bf16 v[34:37], v[154:157], v[170:173], v[34:37]
	v_mfma_f32_16x16x32_bf16 v[42:45], v[146:149], v[178:181], v[42:45]
	v_mfma_f32_16x16x32_bf16 v[50:53], v[154:157], v[178:181], v[50:53]
	v_mfma_f32_16x16x32_bf16 v[58:61], v[146:149], v[188:191], v[58:61]
	v_mfma_f32_16x16x32_bf16 v[62:65], v[154:157], v[188:191], v[62:65]
	v_mfma_f32_16x16x32_bf16 v[10:13], v[150:153], v[166:169], v[10:13]
	v_mfma_f32_16x16x32_bf16 v[18:21], v[158:161], v[166:169], v[18:21]
	v_mfma_f32_16x16x32_bf16 v[26:29], v[150:153], v[174:177], v[26:29]
	v_mfma_f32_16x16x32_bf16 v[34:37], v[158:161], v[174:177], v[34:37]
	v_mfma_f32_16x16x32_bf16 v[42:45], v[150:153], v[182:185], v[42:45]
	v_mfma_f32_16x16x32_bf16 v[50:53], v[158:161], v[182:185], v[50:53]
	v_mfma_f32_16x16x32_bf16 v[58:61], v[150:153], v[192:195], v[58:61]
	v_mfma_f32_16x16x32_bf16 v[62:65], v[158:161], v[192:195], v[62:65]
	s_barrier
	s_mov_b64 s[72:73], s[52:53]
	ds_read_b128 v[162:165], v237 offset:16384
	ds_read_b128 v[166:169], v237 offset:17408
	ds_read_b128 v[170:173], v237 offset:18432
	ds_read_b128 v[174:177], v237 offset:19456
	ds_read_b128 v[178:181], v237 offset:20480
	ds_read_b128 v[182:185], v237 offset:21504
	ds_read_b128 v[188:191], v237 offset:22528
	ds_read_b128 v[192:195], v237 offset:23552
	s_add_i32 s74, s74, s57
	v_lshl_add_u64 v[196:197], s[72:73], 0, v[202:203]
	s_add_u32 s72, s72, 0xb0000
	s_mov_b32 m0, s74
	s_addc_u32 s73, s73, 0
	global_load_lds_dwordx4 v[196:197], off
	s_add_i32 m0, s74, 0x2000
	v_lshl_add_u64 v[196:197], s[72:73], 0, v[202:203]
	s_add_u32 s72, s52, 0x160000
	s_addc_u32 s73, s53, 0
	global_load_lds_dwordx4 v[196:197], off
	s_add_i32 s74, s75, s57
	v_lshl_add_u64 v[196:197], s[72:73], 0, v[202:203]
	s_add_u32 s72, s72, 0xb0000
	s_mov_b32 m0, s74
	s_addc_u32 s73, s73, 0
	global_load_lds_dwordx4 v[196:197], off
	s_add_i32 m0, s74, 0x2000
	v_lshl_add_u64 v[196:197], s[72:73], 0, v[202:203]
	s_mov_b64 s[72:73], s[54:55]
	global_load_lds_dwordx4 v[196:197], off
	s_mov_b32 m0, s58
	v_lshl_add_u64 v[196:197], s[72:73], 0, v[186:187]
	s_add_u32 s72, s72, 0xb0000
	s_addc_u32 s73, s73, 0
	global_load_lds_dwordx4 v[196:197], off
	s_mov_b32 m0, s59
	v_lshl_add_u64 v[196:197], s[72:73], 0, v[186:187]
	global_load_lds_dwordx4 v[196:197], off
	s_waitcnt vmcnt(8)
	s_waitcnt lgkmcnt(0)
	s_barrier
	v_mfma_f32_16x16x32_bf16 v[66:69], v[130:133], v[162:165], v[66:69]
	v_mfma_f32_16x16x32_bf16 v[70:73], v[138:141], v[162:165], v[70:73]
	v_mfma_f32_16x16x32_bf16 v[74:77], v[130:133], v[170:173], v[74:77]
	v_mfma_f32_16x16x32_bf16 v[78:81], v[138:141], v[170:173], v[78:81]
	v_mfma_f32_16x16x32_bf16 v[86:89], v[130:133], v[178:181], v[86:89]
	v_mfma_f32_16x16x32_bf16 v[94:97], v[138:141], v[178:181], v[94:97]
	v_mfma_f32_16x16x32_bf16 v[102:105], v[130:133], v[188:191], v[102:105]
	v_mfma_f32_16x16x32_bf16 v[110:113], v[138:141], v[188:191], v[110:113]
	v_mfma_f32_16x16x32_bf16 v[66:69], v[134:137], v[166:169], v[66:69]
	v_mfma_f32_16x16x32_bf16 v[70:73], v[142:145], v[166:169], v[70:73]
	v_mfma_f32_16x16x32_bf16 v[74:77], v[134:137], v[174:177], v[74:77]
	v_mfma_f32_16x16x32_bf16 v[78:81], v[142:145], v[174:177], v[78:81]
	v_mfma_f32_16x16x32_bf16 v[86:89], v[134:137], v[182:185], v[86:89]
	v_mfma_f32_16x16x32_bf16 v[94:97], v[142:145], v[182:185], v[94:97]
	v_mfma_f32_16x16x32_bf16 v[102:105], v[134:137], v[192:195], v[102:105]
	v_mfma_f32_16x16x32_bf16 v[110:113], v[142:145], v[192:195], v[110:113]
	v_mfma_f32_16x16x32_bf16 v[82:85], v[146:149], v[162:165], v[82:85]
	v_mfma_f32_16x16x32_bf16 v[90:93], v[154:157], v[162:165], v[90:93]
	v_mfma_f32_16x16x32_bf16 v[98:101], v[146:149], v[170:173], v[98:101]
	v_mfma_f32_16x16x32_bf16 v[106:109], v[154:157], v[170:173], v[106:109]
	v_mfma_f32_16x16x32_bf16 v[114:117], v[146:149], v[178:181], v[114:117]
	v_mfma_f32_16x16x32_bf16 v[118:121], v[154:157], v[178:181], v[118:121]
	v_mfma_f32_16x16x32_bf16 v[122:125], v[146:149], v[188:191], v[122:125]
	v_mfma_f32_16x16x32_bf16 v[126:129], v[154:157], v[188:191], v[126:129]
	v_mfma_f32_16x16x32_bf16 v[82:85], v[150:153], v[166:169], v[82:85]
	v_mfma_f32_16x16x32_bf16 v[90:93], v[158:161], v[166:169], v[90:93]
	v_mfma_f32_16x16x32_bf16 v[98:101], v[150:153], v[174:177], v[98:101]
	v_mfma_f32_16x16x32_bf16 v[106:109], v[158:161], v[174:177], v[106:109]
	v_mfma_f32_16x16x32_bf16 v[114:117], v[150:153], v[182:185], v[114:117]
	v_mfma_f32_16x16x32_bf16 v[118:121], v[158:161], v[182:185], v[118:121]
	v_mfma_f32_16x16x32_bf16 v[122:125], v[150:153], v[192:195], v[122:125]
	v_mfma_f32_16x16x32_bf16 v[126:129], v[158:161], v[192:195], v[126:129]
	s_barrier
	s_add_i32 s72, 0, 0x18000
	s_add_i32 s73, 0, 0x1c000
	v_add_u32_e32 v142, s72, v207
	v_add_u32_e32 v158, s73, v207
	ds_read_b128 v[130:133], v142
	ds_read_b128 v[134:137], v142 offset:1024
	ds_read_b128 v[138:141], v142 offset:2048
	ds_read_b128 v[142:145], v142 offset:3072
	ds_read_b128 v[146:149], v158
	ds_read_b128 v[150:153], v158 offset:1024
	ds_read_b128 v[154:157], v158 offset:2048
	ds_read_b128 v[158:161], v158 offset:3072
	s_add_u32 s54, s54, 0x160000
	s_addc_u32 s55, s55, 0
	ds_read_b128 v[162:165], v237 offset:32768
	ds_read_b128 v[166:169], v237 offset:33792
	ds_read_b128 v[170:173], v237 offset:34816
	ds_read_b128 v[174:177], v237 offset:35840
	ds_read_b128 v[178:181], v237 offset:36864
	ds_read_b128 v[182:185], v237 offset:37888
	ds_read_b128 v[188:191], v237 offset:38912
	ds_read_b128 v[192:195], v237 offset:39936
	s_mov_b32 m0, s60
	v_lshl_add_u64 v[196:197], s[54:55], 0, v[186:187]
	s_add_u32 s54, s54, 0xb0000
	s_addc_u32 s55, s55, 0
	global_load_lds_dwordx4 v[196:197], off
	s_mov_b32 m0, s61
	v_lshl_add_u64 v[196:197], s[54:55], 0, v[186:187]
	global_load_lds_dwordx4 v[196:197], off
	s_waitcnt vmcnt(8)
	s_waitcnt lgkmcnt(0)
	s_barrier
	v_mfma_f32_16x16x32_bf16 v[2:5], v[130:133], v[162:165], v[2:5]
	v_mfma_f32_16x16x32_bf16 v[6:9], v[138:141], v[162:165], v[6:9]
	v_mfma_f32_16x16x32_bf16 v[14:17], v[130:133], v[170:173], v[14:17]
	v_mfma_f32_16x16x32_bf16 v[22:25], v[138:141], v[170:173], v[22:25]
	v_mfma_f32_16x16x32_bf16 v[30:33], v[130:133], v[178:181], v[30:33]
	v_mfma_f32_16x16x32_bf16 v[38:41], v[138:141], v[178:181], v[38:41]
	v_mfma_f32_16x16x32_bf16 v[46:49], v[130:133], v[188:191], v[46:49]
	v_mfma_f32_16x16x32_bf16 v[54:57], v[138:141], v[188:191], v[54:57]
	v_mfma_f32_16x16x32_bf16 v[2:5], v[134:137], v[166:169], v[2:5]
	v_mfma_f32_16x16x32_bf16 v[6:9], v[142:145], v[166:169], v[6:9]
	v_mfma_f32_16x16x32_bf16 v[14:17], v[134:137], v[174:177], v[14:17]
	v_mfma_f32_16x16x32_bf16 v[22:25], v[142:145], v[174:177], v[22:25]
	v_mfma_f32_16x16x32_bf16 v[30:33], v[134:137], v[182:185], v[30:33]
	v_mfma_f32_16x16x32_bf16 v[38:41], v[142:145], v[182:185], v[38:41]
	v_mfma_f32_16x16x32_bf16 v[46:49], v[134:137], v[192:195], v[46:49]
	v_mfma_f32_16x16x32_bf16 v[54:57], v[142:145], v[192:195], v[54:57]
	v_mfma_f32_16x16x32_bf16 v[10:13], v[146:149], v[162:165], v[10:13]
	v_mfma_f32_16x16x32_bf16 v[18:21], v[154:157], v[162:165], v[18:21]
	v_mfma_f32_16x16x32_bf16 v[26:29], v[146:149], v[170:173], v[26:29]
	v_mfma_f32_16x16x32_bf16 v[34:37], v[154:157], v[170:173], v[34:37]
	v_mfma_f32_16x16x32_bf16 v[42:45], v[146:149], v[178:181], v[42:45]
	v_mfma_f32_16x16x32_bf16 v[50:53], v[154:157], v[178:181], v[50:53]
	v_mfma_f32_16x16x32_bf16 v[58:61], v[146:149], v[188:191], v[58:61]
	v_mfma_f32_16x16x32_bf16 v[62:65], v[154:157], v[188:191], v[62:65]
	v_mfma_f32_16x16x32_bf16 v[10:13], v[150:153], v[166:169], v[10:13]
	v_mfma_f32_16x16x32_bf16 v[18:21], v[158:161], v[166:169], v[18:21]
	v_mfma_f32_16x16x32_bf16 v[26:29], v[150:153], v[174:177], v[26:29]
	v_mfma_f32_16x16x32_bf16 v[34:37], v[158:161], v[174:177], v[34:37]
	v_mfma_f32_16x16x32_bf16 v[42:45], v[150:153], v[182:185], v[42:45]
	v_mfma_f32_16x16x32_bf16 v[50:53], v[158:161], v[182:185], v[50:53]
	v_mfma_f32_16x16x32_bf16 v[58:61], v[150:153], v[192:195], v[58:61]
	v_mfma_f32_16x16x32_bf16 v[62:65], v[158:161], v[192:195], v[62:65]
	s_barrier
	s_add_u32 s54, s52, 0x80
	s_addc_u32 s55, s53, 0
	ds_read_b128 v[162:165], v237 offset:49152
	ds_read_b128 v[166:169], v237 offset:50176
	ds_read_b128 v[170:173], v237 offset:51200
	ds_read_b128 v[174:177], v237 offset:52224
	ds_read_b128 v[178:181], v237 offset:53248
	ds_read_b128 v[182:185], v237 offset:54272
	ds_read_b128 v[188:191], v237 offset:55296
	ds_read_b128 v[192:195], v237 offset:56320
	s_add_i32 s72, s72, s57
	v_lshl_add_u64 v[196:197], s[54:55], 0, v[202:203]
	s_mov_b32 m0, s72
	s_add_u32 s54, s54, 0xb0000
	global_load_lds_dwordx4 v[196:197], off
	s_addc_u32 s55, s55, 0
	s_add_i32 m0, s72, 0x2000
	s_add_u32 s52, s52, 0x160080
	s_addc_u32 s53, s53, 0
	v_lshl_add_u64 v[196:197], s[54:55], 0, v[202:203]
	global_load_lds_dwordx4 v[196:197], off
	s_add_i32 s54, s73, s57
	v_lshl_add_u64 v[196:197], s[52:53], 0, v[202:203]
	s_add_u32 s52, s52, 0xb0000
	s_mov_b32 m0, s54
	s_addc_u32 s53, s53, 0
	global_load_lds_dwordx4 v[196:197], off
	s_add_i32 m0, s54, 0x2000
	v_lshl_add_u64 v[196:197], s[52:53], 0, v[202:203]
	global_load_lds_dwordx4 v[196:197], off
	s_mov_b32 m0, s62
	v_lshl_add_u64 v[196:197], s[46:47], 0, v[186:187]
	s_add_u32 s46, s46, 0xb0000
	s_addc_u32 s47, s47, 0
	global_load_lds_dwordx4 v[196:197], off
	s_mov_b32 m0, s63
	v_lshl_add_u64 v[196:197], s[46:47], 0, v[186:187]
	global_load_lds_dwordx4 v[196:197], off
	s_waitcnt vmcnt(8)
	s_waitcnt lgkmcnt(0)
	s_barrier
	v_mfma_f32_16x16x32_bf16 v[66:69], v[130:133], v[162:165], v[66:69]
	v_mfma_f32_16x16x32_bf16 v[70:73], v[138:141], v[162:165], v[70:73]
	v_mfma_f32_16x16x32_bf16 v[74:77], v[130:133], v[170:173], v[74:77]
	v_mfma_f32_16x16x32_bf16 v[78:81], v[138:141], v[170:173], v[78:81]
	v_mfma_f32_16x16x32_bf16 v[86:89], v[130:133], v[178:181], v[86:89]
	v_mfma_f32_16x16x32_bf16 v[94:97], v[138:141], v[178:181], v[94:97]
	v_mfma_f32_16x16x32_bf16 v[102:105], v[130:133], v[188:191], v[102:105]
	v_mfma_f32_16x16x32_bf16 v[110:113], v[138:141], v[188:191], v[110:113]
	v_mfma_f32_16x16x32_bf16 v[66:69], v[134:137], v[166:169], v[66:69]
	v_mfma_f32_16x16x32_bf16 v[70:73], v[142:145], v[166:169], v[70:73]
	v_mfma_f32_16x16x32_bf16 v[74:77], v[134:137], v[174:177], v[74:77]
	v_mfma_f32_16x16x32_bf16 v[78:81], v[142:145], v[174:177], v[78:81]
	v_mfma_f32_16x16x32_bf16 v[86:89], v[134:137], v[182:185], v[86:89]
	v_mfma_f32_16x16x32_bf16 v[94:97], v[142:145], v[182:185], v[94:97]
	v_mfma_f32_16x16x32_bf16 v[102:105], v[134:137], v[192:195], v[102:105]
	v_mfma_f32_16x16x32_bf16 v[110:113], v[142:145], v[192:195], v[110:113]
	v_mfma_f32_16x16x32_bf16 v[82:85], v[146:149], v[162:165], v[82:85]
	v_mfma_f32_16x16x32_bf16 v[90:93], v[154:157], v[162:165], v[90:93]
	v_mfma_f32_16x16x32_bf16 v[98:101], v[146:149], v[170:173], v[98:101]
	v_mfma_f32_16x16x32_bf16 v[106:109], v[154:157], v[170:173], v[106:109]
	v_mfma_f32_16x16x32_bf16 v[114:117], v[146:149], v[178:181], v[114:117]
	v_mfma_f32_16x16x32_bf16 v[118:121], v[154:157], v[178:181], v[118:121]
	v_mfma_f32_16x16x32_bf16 v[122:125], v[146:149], v[188:191], v[122:125]
	v_mfma_f32_16x16x32_bf16 v[126:129], v[154:157], v[188:191], v[126:129]
	v_mfma_f32_16x16x32_bf16 v[82:85], v[150:153], v[166:169], v[82:85]
	v_mfma_f32_16x16x32_bf16 v[90:93], v[158:161], v[166:169], v[90:93]
	v_mfma_f32_16x16x32_bf16 v[98:101], v[150:153], v[174:177], v[98:101]
	v_mfma_f32_16x16x32_bf16 v[106:109], v[158:161], v[174:177], v[106:109]
	v_mfma_f32_16x16x32_bf16 v[114:117], v[150:153], v[182:185], v[114:117]
	v_mfma_f32_16x16x32_bf16 v[118:121], v[158:161], v[182:185], v[118:121]
	v_mfma_f32_16x16x32_bf16 v[122:125], v[150:153], v[192:195], v[122:125]
	v_mfma_f32_16x16x32_bf16 v[126:129], v[158:161], v[192:195], v[126:129]
	s_barrier
	s_add_i32 s71, s71, 2
	s_add_u32 s9, s9, 0x100
	s_addc_u32 s27, s27, 0
	s_add_u32 s28, s28, 0x100
	s_addc_u32 s29, s29, 0
	s_add_u32 s44, s44, 0x100
	s_addc_u32 s45, s45, 0
	s_cmpk_gt_u32 s71, 0x55
	s_cbranch_scc0 .LBB0_1286
	s_and_b64 vcc, exec, s[18:19]
	s_cbranch_vccz .LBB0_1289
	s_barrier
